# EpiProj silu variants: -log2e multiply and +1.0 add in packed f32 form, computed in place in the result registers (32 sites)
# speedup vs baseline: 1.0181x; 1.0017x over previous
; #define PG8_STAGE(bufoff, gbase, voff) do { _Pragma("unroll") for (int _i = 0; _i < 2; ++_i) \
;         __builtin_amdgcn_global_load_lds((const unsigned*)((const char*)(gbase) + (voff)[_i]), (PG8_LAS unsigned*)(lds + (bufoff) + ldsw + _i * 8192), 16, 0, 0); } while (0)
; #define PG8_LDA(dst, b, h) do { _Pragma("unroll") for (int m = 0; m < 4; ++m) _Pragma("unroll") for (int k = 0; k < 2; ++k) dst[m][k] = *(const PG8_LAS bf16x8*)(lds + PG8_SA(b, h) + aoff + m * 2048 + k * 1024); } while (0)
; #define PG8_LDB(dst, b, h) do { _Pragma("unroll") for (int n = 0; n < 2; ++n) _Pragma("unroll") for (int k = 0; k < 2; ++k) dst[n][k] = *(const PG8_LAS bf16x8*)(lds + PG8_SB(b, h) + boff + n * 2048 + k * 1024); } while (0)
; #define PG8_MMA(ai, bj, At, Bt) do { __builtin_amdgcn_s_setprio(1); _Pragma("unroll") for (int m = 0; m < 4; ++m) _Pragma("unroll") for (int n = 0; n < 2; ++n) _Pragma("unroll") for (int k = 0; k < 2; ++k) \
;         acc[ai][bj][m][n] = __builtin_amdgcn_mfma_f32_16x16x32_bf16(Bt[n][k], At[m][k], acc[ai][bj][m][n], 0, 0, 0); __builtin_amdgcn_s_setprio(0); } while (0)
; #define PG8_WAIT_V(n) asm volatile("s_waitcnt vmcnt(" #n ")" ::: "memory")
; #define PG8_WAIT_L(n) asm volatile("s_waitcnt lgkmcnt(" #n ")" ::: "memory")
; template <class Epi, class Sched, bool ALIGN_EPI = false, bool SP2 = false>
; __device__ __forceinline__ void gemm_phase(PG8_LAS unsigned char* lds, const Gemm g, const Sched& S, const Epi& E) {
;     ...
;             const bool last = (t == nt - 2);
;             const char* a1 = cA + (size_t)(t + 1) * kstep;
;             const char* a2 = last ? nA : cA + (size_t)(t + 2) * kstep; const char* b2 = last ? nB : cB + (size_t)(t + 2) * kstep;
;             const char* a3 = a2 + kstep; const char* b3 = b2 + kstep;
;             if (last && has_next) S.a_ready(nxt);
;             if constexpr (SP2) {
;             PG8_LDB(B0, 0, 0); PG8_LDB(B1, 0, 1); PG8_SCHED; PG8_LDA(At, 0, 0); PG8_STAGE(PG8_SA(1, 1), a1 + hstep, voffA);
;             PG8_WAIT_V(8); PG8_WAIT_L(0); PG8_BAR; PG8_MMA(0, 0, At, B0); PG8_MMA(0, 1, At, B1); PG8_BAR; PG8_SCHED;
;             PG8_LDA(At, 0, 1); PG8_STAGE(PG8_SB(0, 0), b2, voffB); PG8_STAGE(PG8_SB(0, 1), b2 + hstep, voffB); PG8_STAGE(PG8_SA(0, 0), a2, voffA);
;             PG8_WAIT_V(8); PG8_WAIT_L(0); PG8_BAR; PG8_MMA(1, 0, At, B0); PG8_MMA(1, 1, At, B1); PG8_BAR; PG8_SCHED;
.LBB0_110:
	ds_read_b128 v[146:149], v160
	ds_read_b128 v[150:153], v160 offset:1024
	ds_read_b128 v[154:157], v160 offset:2048
	ds_read_b128 v[166:169], v160 offset:3072
	ds_read_b128 v[170:173], v161
	ds_read_b128 v[174:177], v161 offset:1024
	ds_read_b128 v[178:181], v161 offset:2048
	ds_read_b128 v[182:185], v161 offset:3072
	s_add_u32 s8, s6, 0xfffc0080
	s_addc_u32 s9, s7, -1
	s_cmp_eq_u32 s84, 12
	s_cselect_b32 s83, s1, s9
	s_cselect_b32 s82, s33, s8
	s_cselect_b32 s9, s60, s75
	s_cselect_b32 s8, s61, s73
	v_lshl_add_u64 v[220:221], s[6:7], 0, v[138:139]
	s_add_i32 m0, s81, 0xc000
	ds_read_b128 v[186:189], v162
	ds_read_b128 v[190:193], v162 offset:1024
	ds_read_b128 v[194:197], v162 offset:2048
	ds_read_b128 v[198:201], v162 offset:3072
	ds_read_b128 v[202:205], v162 offset:4096
	ds_read_b128 v[208:211], v162 offset:5120
	ds_read_b128 v[212:215], v162 offset:6144
	ds_read_b128 v[216:219], v162 offset:7168
	global_load_lds_dwordx4 v[220:221], off
	v_lshl_add_u64 v[220:221], s[6:7], 0, v[140:141]
	s_add_i32 m0, s81, 0xe000
	s_nop 0
	global_load_lds_dwordx4 v[220:221], off
	s_waitcnt vmcnt(8)
	s_waitcnt lgkmcnt(0)
	s_barrier
	s_setprio 1
	s_waitcnt lgkmcnt(0)
	v_mfma_f32_16x16x32_bf16 v[126:129], v[146:149], v[186:189], v[126:129]
	v_mfma_f32_16x16x32_bf16 v[122:125], v[154:157], v[186:189], v[122:125]
	v_mfma_f32_16x16x32_bf16 v[118:121], v[146:149], v[194:197], v[118:121]
	v_mfma_f32_16x16x32_bf16 v[114:117], v[154:157], v[194:197], v[114:117]
	v_mfma_f32_16x16x32_bf16 v[110:113], v[146:149], v[202:205], v[110:113]
	v_mfma_f32_16x16x32_bf16 v[106:109], v[154:157], v[202:205], v[106:109]
	v_mfma_f32_16x16x32_bf16 v[102:105], v[146:149], v[212:215], v[102:105]
	v_mfma_f32_16x16x32_bf16 v[98:101], v[154:157], v[212:215], v[98:101]
	v_mfma_f32_16x16x32_bf16 v[126:129], v[150:153], v[190:193], v[126:129]
	v_mfma_f32_16x16x32_bf16 v[122:125], v[166:169], v[190:193], v[122:125]
	v_mfma_f32_16x16x32_bf16 v[118:121], v[150:153], v[198:201], v[118:121]
	v_mfma_f32_16x16x32_bf16 v[114:117], v[166:169], v[198:201], v[114:117]
	v_mfma_f32_16x16x32_bf16 v[110:113], v[150:153], v[208:211], v[110:113]
	v_mfma_f32_16x16x32_bf16 v[106:109], v[166:169], v[208:211], v[106:109]
	v_mfma_f32_16x16x32_bf16 v[102:105], v[150:153], v[216:219], v[102:105]
	v_mfma_f32_16x16x32_bf16 v[98:101], v[166:169], v[216:219], v[98:101]
	s_setprio 0
	s_setprio 1
	v_mfma_f32_16x16x32_bf16 v[62:65], v[170:173], v[186:189], v[62:65]
	v_mfma_f32_16x16x32_bf16 v[58:61], v[178:181], v[186:189], v[58:61]
	v_mfma_f32_16x16x32_bf16 v[54:57], v[170:173], v[194:197], v[54:57]
	v_mfma_f32_16x16x32_bf16 v[50:53], v[178:181], v[194:197], v[50:53]
	v_mfma_f32_16x16x32_bf16 v[46:49], v[170:173], v[202:205], v[46:49]
	v_mfma_f32_16x16x32_bf16 v[42:45], v[178:181], v[202:205], v[42:45]
	v_mfma_f32_16x16x32_bf16 v[38:41], v[170:173], v[212:215], v[38:41]
	v_mfma_f32_16x16x32_bf16 v[34:37], v[178:181], v[212:215], v[34:37]
	v_mfma_f32_16x16x32_bf16 v[62:65], v[174:177], v[190:193], v[62:65]
	v_mfma_f32_16x16x32_bf16 v[58:61], v[182:185], v[190:193], v[58:61]
	v_mfma_f32_16x16x32_bf16 v[54:57], v[174:177], v[198:201], v[54:57]
	v_mfma_f32_16x16x32_bf16 v[50:53], v[182:185], v[198:201], v[50:53]
	v_mfma_f32_16x16x32_bf16 v[46:49], v[174:177], v[208:211], v[46:49]
	v_mfma_f32_16x16x32_bf16 v[42:45], v[182:185], v[208:211], v[42:45]
	v_mfma_f32_16x16x32_bf16 v[38:41], v[174:177], v[216:219], v[38:41]
	v_mfma_f32_16x16x32_bf16 v[34:37], v[182:185], v[216:219], v[34:37]
	s_setprio 0
	s_barrier
	s_add_i32 s85, s30, s87
	s_mov_b32 m0, s85
	ds_read_b128 v[186:189], v162 offset:16384
	ds_read_b128 v[190:193], v162 offset:17408
	ds_read_b128 v[194:197], v162 offset:18432
	ds_read_b128 v[198:201], v162 offset:19456
	ds_read_b128 v[202:205], v162 offset:20480
	ds_read_b128 v[208:211], v162 offset:21504
	ds_read_b128 v[212:215], v162 offset:22528
	ds_read_b128 v[216:219], v162 offset:23552
	global_load_lds_dwordx4 v132, s[8:9]
	s_add_i32 m0, s85, 0x2000
	s_add_u32 vcc_lo, s8, 0x40000
	v_lshl_add_u64 v[222:223], s[8:9], 0, v[136:137]
	s_addc_u32 vcc_hi, s9, 0
	s_add_i32 s85, s31, s87
	global_load_lds_dwordx4 v136, s[8:9]
	s_mov_b32 m0, s85
	v_lshl_add_u64 v[226:227], s[82:83], 0, v[134:135]
	global_load_lds_dwordx4 v132, vcc
	s_add_i32 m0, s85, 0x2000
	s_nop 0
	global_load_lds_dwordx4 v136, vcc
	v_lshl_add_u64 v[224:225], s[82:83], 0, v[130:131]
	s_mov_b32 m0, s81
	s_nop 0
	global_load_lds_dwordx4 v130, s[82:83]
	s_mov_b32 m0, s88
	s_nop 0
	global_load_lds_dwordx4 v134, s[82:83]
	s_waitcnt vmcnt(8)
	s_waitcnt lgkmcnt(0)
	s_barrier
; #define PG8_STAGE(bufoff, gbase, voff) do { _Pragma("unroll") for (int _i = 0; _i < 2; ++_i) \
;         __builtin_amdgcn_global_load_lds((const unsigned*)((const char*)(gbase) + (voff)[_i]), (PG8_LAS unsigned*)(lds + (bufoff) + ldsw + _i * 8192), 16, 0, 0); } while (0)
; #define PG8_LDA(dst, b, h) do { _Pragma("unroll") for (int m = 0; m < 4; ++m) _Pragma("unroll") for (int k = 0; k < 2; ++k) dst[m][k] = *(const PG8_LAS bf16x8*)(lds + PG8_SA(b, h) + aoff + m * 2048 + k * 1024); } while (0)
; #define PG8_LDB(dst, b, h) do { _Pragma("unroll") for (int n = 0; n < 2; ++n) _Pragma("unroll") for (int k = 0; k < 2; ++k) dst[n][k] = *(const PG8_LAS bf16x8*)(lds + PG8_SB(b, h) + boff + n * 2048 + k * 1024); } while (0)
; #define PG8_MMA(ai, bj, At, Bt) do { __builtin_amdgcn_s_setprio(1); _Pragma("unroll") for (int m = 0; m < 4; ++m) _Pragma("unroll") for (int n = 0; n < 2; ++n) _Pragma("unroll") for (int k = 0; k < 2; ++k) \
;         acc[ai][bj][m][n] = __builtin_amdgcn_mfma_f32_16x16x32_bf16(Bt[n][k], At[m][k], acc[ai][bj][m][n], 0, 0, 0); __builtin_amdgcn_s_setprio(0); } while (0)
; #define PG8_WAIT_V(n) asm volatile("s_waitcnt vmcnt(" #n ")" ::: "memory")
; #define PG8_WAIT_L(n) asm volatile("s_waitcnt lgkmcnt(" #n ")" ::: "memory")
; #define PG8_BAR __builtin_amdgcn_s_barrier()
; #define PG8_SCHED __builtin_amdgcn_sched_barrier(0)
; template <class Epi, class Sched, bool ALIGN_EPI = false, bool SP2 = false>
; __device__ __forceinline__ void gemm_phase(PG8_LAS unsigned char* lds, const Gemm g, const Sched& S, const Epi& E) {
;     ...
;             PG8_WAIT_V(8); PG8_WAIT_L(0); PG8_BAR; PG8_MMA(1, 0, At, B0); PG8_MMA(1, 1, At, B1); PG8_BAR; PG8_SCHED;
;             PG8_LDB(B0, 1, 0); PG8_LDB(B1, 1, 1); PG8_SCHED; PG8_LDA(At, 1, 0); PG8_STAGE(PG8_SA(0, 1), a2 + hstep, voffA);
;             PG8_WAIT_V(8); PG8_WAIT_L(0); PG8_BAR; PG8_MMA(0, 0, At, B0); PG8_MMA(0, 1, At, B1); PG8_BAR; PG8_SCHED;
	s_setprio 1
	s_waitcnt lgkmcnt(0)
	v_mfma_f32_16x16x32_bf16 v[94:97], v[146:149], v[186:189], v[94:97]
	v_mfma_f32_16x16x32_bf16 v[90:93], v[154:157], v[186:189], v[90:93]
	v_mfma_f32_16x16x32_bf16 v[86:89], v[146:149], v[194:197], v[86:89]
	v_mfma_f32_16x16x32_bf16 v[82:85], v[154:157], v[194:197], v[82:85]
	v_mfma_f32_16x16x32_bf16 v[78:81], v[146:149], v[202:205], v[78:81]
	v_mfma_f32_16x16x32_bf16 v[74:77], v[154:157], v[202:205], v[74:77]
	v_mfma_f32_16x16x32_bf16 v[70:73], v[146:149], v[212:215], v[70:73]
	v_mfma_f32_16x16x32_bf16 v[66:69], v[154:157], v[212:215], v[66:69]
	v_mfma_f32_16x16x32_bf16 v[94:97], v[150:153], v[190:193], v[94:97]
	v_mfma_f32_16x16x32_bf16 v[90:93], v[166:169], v[190:193], v[90:93]
	v_mfma_f32_16x16x32_bf16 v[86:89], v[150:153], v[198:201], v[86:89]
	v_mfma_f32_16x16x32_bf16 v[82:85], v[166:169], v[198:201], v[82:85]
	v_mfma_f32_16x16x32_bf16 v[78:81], v[150:153], v[208:211], v[78:81]
	v_mfma_f32_16x16x32_bf16 v[74:77], v[166:169], v[208:211], v[74:77]
	v_mfma_f32_16x16x32_bf16 v[70:73], v[150:153], v[216:219], v[70:73]
	v_mfma_f32_16x16x32_bf16 v[66:69], v[166:169], v[216:219], v[66:69]
	s_setprio 0
	s_setprio 1
	v_mfma_f32_16x16x32_bf16 v[30:33], v[170:173], v[186:189], v[30:33]
	v_mfma_f32_16x16x32_bf16 v[26:29], v[178:181], v[186:189], v[26:29]
	v_mfma_f32_16x16x32_bf16 v[22:25], v[170:173], v[194:197], v[22:25]
	v_mfma_f32_16x16x32_bf16 v[18:21], v[178:181], v[194:197], v[18:21]
	v_mfma_f32_16x16x32_bf16 v[14:17], v[170:173], v[202:205], v[14:17]
	v_mfma_f32_16x16x32_bf16 v[10:13], v[178:181], v[202:205], v[10:13]
	v_mfma_f32_16x16x32_bf16 v[6:9], v[170:173], v[212:215], v[6:9]
	v_mfma_f32_16x16x32_bf16 v[2:5], v[178:181], v[212:215], v[2:5]
	v_mfma_f32_16x16x32_bf16 v[30:33], v[174:177], v[190:193], v[30:33]
	v_mfma_f32_16x16x32_bf16 v[26:29], v[182:185], v[190:193], v[26:29]
	v_mfma_f32_16x16x32_bf16 v[22:25], v[174:177], v[198:201], v[22:25]
	v_mfma_f32_16x16x32_bf16 v[18:21], v[182:185], v[198:201], v[18:21]
	v_mfma_f32_16x16x32_bf16 v[14:17], v[174:177], v[208:211], v[14:17]
	v_mfma_f32_16x16x32_bf16 v[10:13], v[182:185], v[208:211], v[10:13]
	v_mfma_f32_16x16x32_bf16 v[6:9], v[174:177], v[216:219], v[6:9]
	v_mfma_f32_16x16x32_bf16 v[2:5], v[182:185], v[216:219], v[2:5]
	s_setprio 0
	s_barrier
	s_add_i32 s85, 0, 0x18000
	v_add_u32_e32 v165, s85, v158
	s_add_i32 vcc_lo, 0, 0x1c000
	ds_read_b128 v[146:149], v165
	ds_read_b128 v[150:153], v165 offset:1024
	ds_read_b128 v[154:157], v165 offset:2048
	ds_read_b128 v[166:169], v165 offset:3072
	v_add_u32_e32 v165, vcc_lo, v158
	ds_read_b128 v[170:173], v165
	ds_read_b128 v[174:177], v165 offset:1024
	ds_read_b128 v[178:181], v165 offset:2048
	ds_read_b128 v[182:185], v165 offset:3072
	s_add_u32 s82, s82, 0x40000
	s_addc_u32 s83, s83, 0
	s_mov_b32 m0, s89
	ds_read_b128 v[186:189], v162 offset:32768
	ds_read_b128 v[190:193], v162 offset:33792
	ds_read_b128 v[194:197], v162 offset:34816
	ds_read_b128 v[198:201], v162 offset:35840
	ds_read_b128 v[202:205], v162 offset:36864
	ds_read_b128 v[208:211], v162 offset:37888
	ds_read_b128 v[212:215], v162 offset:38912
	ds_read_b128 v[216:219], v162 offset:39936
	global_load_lds_dwordx4 v130, s[82:83]
	s_mov_b32 m0, s90
	s_nop 0
	global_load_lds_dwordx4 v134, s[82:83]
	s_waitcnt vmcnt(8)
	s_waitcnt lgkmcnt(0)
	s_barrier
	s_setprio 1
	s_waitcnt lgkmcnt(0)
	v_mfma_f32_16x16x32_bf16 v[126:129], v[146:149], v[186:189], v[126:129]
	v_mfma_f32_16x16x32_bf16 v[122:125], v[154:157], v[186:189], v[122:125]
	v_mfma_f32_16x16x32_bf16 v[118:121], v[146:149], v[194:197], v[118:121]
	v_mfma_f32_16x16x32_bf16 v[114:117], v[154:157], v[194:197], v[114:117]
	v_mfma_f32_16x16x32_bf16 v[110:113], v[146:149], v[202:205], v[110:113]
	v_mfma_f32_16x16x32_bf16 v[106:109], v[154:157], v[202:205], v[106:109]
	v_mfma_f32_16x16x32_bf16 v[102:105], v[146:149], v[212:215], v[102:105]
	v_mfma_f32_16x16x32_bf16 v[98:101], v[154:157], v[212:215], v[98:101]
	v_mfma_f32_16x16x32_bf16 v[126:129], v[150:153], v[190:193], v[126:129]
	v_mfma_f32_16x16x32_bf16 v[122:125], v[166:169], v[190:193], v[122:125]
	v_mfma_f32_16x16x32_bf16 v[118:121], v[150:153], v[198:201], v[118:121]
	v_mfma_f32_16x16x32_bf16 v[114:117], v[166:169], v[198:201], v[114:117]
	v_mfma_f32_16x16x32_bf16 v[110:113], v[150:153], v[208:211], v[110:113]
	v_mfma_f32_16x16x32_bf16 v[106:109], v[166:169], v[208:211], v[106:109]
	v_mfma_f32_16x16x32_bf16 v[102:105], v[150:153], v[216:219], v[102:105]
	v_mfma_f32_16x16x32_bf16 v[98:101], v[166:169], v[216:219], v[98:101]
	s_setprio 0
	s_setprio 1
	v_mfma_f32_16x16x32_bf16 v[62:65], v[170:173], v[186:189], v[62:65]
	v_mfma_f32_16x16x32_bf16 v[58:61], v[178:181], v[186:189], v[58:61]
	v_mfma_f32_16x16x32_bf16 v[54:57], v[170:173], v[194:197], v[54:57]
	v_mfma_f32_16x16x32_bf16 v[50:53], v[178:181], v[194:197], v[50:53]
	v_mfma_f32_16x16x32_bf16 v[46:49], v[170:173], v[202:205], v[46:49]
	v_mfma_f32_16x16x32_bf16 v[42:45], v[178:181], v[202:205], v[42:45]
	v_mfma_f32_16x16x32_bf16 v[38:41], v[170:173], v[212:215], v[38:41]
	v_mfma_f32_16x16x32_bf16 v[34:37], v[178:181], v[212:215], v[34:37]
	v_mfma_f32_16x16x32_bf16 v[62:65], v[174:177], v[190:193], v[62:65]
	v_mfma_f32_16x16x32_bf16 v[58:61], v[182:185], v[190:193], v[58:61]
	v_mfma_f32_16x16x32_bf16 v[54:57], v[174:177], v[198:201], v[54:57]
	v_mfma_f32_16x16x32_bf16 v[50:53], v[182:185], v[198:201], v[50:53]
	v_mfma_f32_16x16x32_bf16 v[46:49], v[174:177], v[208:211], v[46:49]
	v_mfma_f32_16x16x32_bf16 v[42:45], v[182:185], v[208:211], v[42:45]
	v_mfma_f32_16x16x32_bf16 v[38:41], v[174:177], v[216:219], v[38:41]
	v_mfma_f32_16x16x32_bf16 v[34:37], v[182:185], v[216:219], v[34:37]
	s_setprio 0
	s_barrier
; #define PG8_STAGE(bufoff, gbase, voff) do { _Pragma("unroll") for (int _i = 0; _i < 2; ++_i) \
;         __builtin_amdgcn_global_load_lds((const unsigned*)((const char*)(gbase) + (voff)[_i]), (PG8_LAS unsigned*)(lds + (bufoff) + ldsw + _i * 8192), 16, 0, 0); } while (0)
; #define PG8_LDA(dst, b, h) do { _Pragma("unroll") for (int m = 0; m < 4; ++m) _Pragma("unroll") for (int k = 0; k < 2; ++k) dst[m][k] = *(const PG8_LAS bf16x8*)(lds + PG8_SA(b, h) + aoff + m * 2048 + k * 1024); } while (0)
; #define PG8_MMA(ai, bj, At, Bt) do { __builtin_amdgcn_s_setprio(1); _Pragma("unroll") for (int m = 0; m < 4; ++m) _Pragma("unroll") for (int n = 0; n < 2; ++n) _Pragma("unroll") for (int k = 0; k < 2; ++k) \
;         acc[ai][bj][m][n] = __builtin_amdgcn_mfma_f32_16x16x32_bf16(Bt[n][k], At[m][k], acc[ai][bj][m][n], 0, 0, 0); __builtin_amdgcn_s_setprio(0); } while (0)
; #define PG8_WAIT_V(n) asm volatile("s_waitcnt vmcnt(" #n ")" ::: "memory")
; #define PG8_WAIT_L(n) asm volatile("s_waitcnt lgkmcnt(" #n ")" ::: "memory")
; #define PG8_BAR __builtin_amdgcn_s_barrier()
; #define PG8_SCHED __builtin_amdgcn_sched_barrier(0)
; template <class Epi, class Sched, bool ALIGN_EPI = false, bool SP2 = false>
; __device__ __forceinline__ void gemm_phase(PG8_LAS unsigned char* lds, const Gemm g, const Sched& S, const Epi& E) {
;     ...
;             PG8_LDA(At, 1, 1); PG8_STAGE(PG8_SB(1, 0), b3, voffB); PG8_STAGE(PG8_SB(1, 1), b3 + hstep, voffB); PG8_STAGE(PG8_SA(1, 0), a3, voffA);
;             PG8_WAIT_V(8); PG8_WAIT_L(0); PG8_BAR; PG8_MMA(1, 0, At, B0); PG8_MMA(1, 1, At, B1); PG8_BAR; PG8_SCHED;
;     ...
;         if constexpr (ALIGN_EPI) { if (wr == 0) PG8_BAR; }
	s_add_i32 s82, s85, s87
	s_mov_b32 m0, s82
	ds_read_b128 v[186:189], v162 offset:49152
	ds_read_b128 v[190:193], v162 offset:50176
	ds_read_b128 v[194:197], v162 offset:51200
	ds_read_b128 v[198:201], v162 offset:52224
	ds_read_b128 v[202:205], v162 offset:53248
	ds_read_b128 v[208:211], v162 offset:54272
	ds_read_b128 v[212:215], v162 offset:55296
	ds_read_b128 v[216:219], v162 offset:56320
	s_add_u32 s98, s8, s26
	s_addc_u32 s99, s9, s27
	global_load_lds_dwordx4 v132, s[98:99]
	s_add_i32 m0, s82, 0x2000
	s_add_u32 s8, s8, 0x40080
	v_lshl_add_u64 v[220:221], v[222:223], 0, s[26:27]
	s_addc_u32 s9, s9, 0
	s_add_i32 s82, vcc_lo, s87
	global_load_lds_dwordx4 v[220:221], off
	s_mov_b32 m0, s82
	s_nop 0
	global_load_lds_dwordx4 v132, s[8:9]
	s_add_i32 m0, s82, 0x2000
	s_nop 0
	global_load_lds_dwordx4 v136, s[8:9]
	v_lshl_add_u64 v[220:221], v[224:225], 0, s[26:27]
	s_mov_b32 m0, s92
	s_nop 0
	global_load_lds_dwordx4 v[220:221], off
	v_lshl_add_u64 v[220:221], v[226:227], 0, s[26:27]
	s_mov_b32 m0, s93
	s_nop 0
	global_load_lds_dwordx4 v[220:221], off
	s_waitcnt vmcnt(8)
	s_waitcnt lgkmcnt(0)
	s_barrier
	s_setprio 1
	s_waitcnt lgkmcnt(0)
	v_mfma_f32_16x16x32_bf16 v[94:97], v[146:149], v[186:189], v[94:97]
	v_mfma_f32_16x16x32_bf16 v[90:93], v[154:157], v[186:189], v[90:93]
	v_mfma_f32_16x16x32_bf16 v[86:89], v[146:149], v[194:197], v[86:89]
	v_mfma_f32_16x16x32_bf16 v[82:85], v[154:157], v[194:197], v[82:85]
	v_mfma_f32_16x16x32_bf16 v[78:81], v[146:149], v[202:205], v[78:81]
	v_mfma_f32_16x16x32_bf16 v[74:77], v[154:157], v[202:205], v[74:77]
	v_mfma_f32_16x16x32_bf16 v[70:73], v[146:149], v[212:215], v[70:73]
	v_mfma_f32_16x16x32_bf16 v[66:69], v[154:157], v[212:215], v[66:69]
	v_mfma_f32_16x16x32_bf16 v[94:97], v[150:153], v[190:193], v[94:97]
	v_mfma_f32_16x16x32_bf16 v[90:93], v[166:169], v[190:193], v[90:93]
	v_mfma_f32_16x16x32_bf16 v[86:89], v[150:153], v[198:201], v[86:89]
	v_mfma_f32_16x16x32_bf16 v[82:85], v[166:169], v[198:201], v[82:85]
	v_mfma_f32_16x16x32_bf16 v[78:81], v[150:153], v[208:211], v[78:81]
	v_mfma_f32_16x16x32_bf16 v[74:77], v[166:169], v[208:211], v[74:77]
	v_mfma_f32_16x16x32_bf16 v[70:73], v[150:153], v[216:219], v[70:73]
	v_mfma_f32_16x16x32_bf16 v[66:69], v[166:169], v[216:219], v[66:69]
	s_setprio 0
	s_setprio 1
	v_mfma_f32_16x16x32_bf16 v[30:33], v[170:173], v[186:189], v[30:33]
	v_mfma_f32_16x16x32_bf16 v[26:29], v[178:181], v[186:189], v[26:29]
	v_mfma_f32_16x16x32_bf16 v[22:25], v[170:173], v[194:197], v[22:25]
	v_mfma_f32_16x16x32_bf16 v[18:21], v[178:181], v[194:197], v[18:21]
	v_mfma_f32_16x16x32_bf16 v[14:17], v[170:173], v[202:205], v[14:17]
	v_mfma_f32_16x16x32_bf16 v[10:13], v[178:181], v[202:205], v[10:13]
	v_mfma_f32_16x16x32_bf16 v[6:9], v[170:173], v[212:215], v[6:9]
	v_mfma_f32_16x16x32_bf16 v[2:5], v[178:181], v[212:215], v[2:5]
	v_mfma_f32_16x16x32_bf16 v[30:33], v[174:177], v[190:193], v[30:33]
	v_mfma_f32_16x16x32_bf16 v[26:29], v[182:185], v[190:193], v[26:29]
	v_mfma_f32_16x16x32_bf16 v[22:25], v[174:177], v[198:201], v[22:25]
	v_mfma_f32_16x16x32_bf16 v[18:21], v[182:185], v[198:201], v[18:21]
	v_mfma_f32_16x16x32_bf16 v[14:17], v[174:177], v[208:211], v[14:17]
	v_mfma_f32_16x16x32_bf16 v[10:13], v[182:185], v[208:211], v[10:13]
	v_mfma_f32_16x16x32_bf16 v[6:9], v[174:177], v[216:219], v[6:9]
	v_mfma_f32_16x16x32_bf16 v[2:5], v[182:185], v[216:219], v[2:5]
	s_setprio 0
	s_add_i32 s84, s84, 2
	s_add_u32 s6, s6, 0x100
	s_addc_u32 s7, s7, 0
	s_add_u32 s73, s73, 0x100
	s_addc_u32 s75, s75, 0
	s_cmp_gt_u32 s84, 13
	s_barrier
	s_cbranch_scc0 .LBB0_110
	s_mov_b32 s100, 0xbfb8aa3b
	s_mov_b32 s98, 1.0
	s_and_b64 vcc, exec, s[68:69]
	s_cbranch_vccz .LBB0_113
	s_barrier

;     __device__ __forceinline__ void operator()(const f32x4 (&acc)[2][2][4][2], const Unit& u, int wr, int wc, int fr, int fq) const {
;     ...
;                     const int row = row0 + ai * HALF + m * 16; const float rs = rsc ? rsc[row - rbase] : rstd[row];
;                     float v[8];
; #pragma unroll
;                     for (int i = 0; i < 4; ++i) { v[i] = acc[ai][bj][m][0][i] * rs; v[4 + i] = acc[ai][bj][m][1][i] * rs; }
;                     if (seg == 0) {
; #pragma unroll
;                         for (int i = 0; i < 8; ++i) v[i] = v[i] * __builtin_amdgcn_rcpf(1.0f + __expf(-v[i])) * 0.08838834764831845f;
;                     } else if (seg == 1) {
; #pragma unroll
;                         for (int i = 0; i < 8; ++i) { const float s = __builtin_amdgcn_rcpf(1.0f + __expf(-v[i])); v[i] = __logf(lb[i] + (1.0f - lb[i]) * s); }
;                     } else if (seg == 3) {
; #pragma unroll
;                         for (int i = 0; i < 8; ++i) v[i] = v[i] * __builtin_amdgcn_rcpf(1.0f + __expf(-v[i]));
;                     }
.LBB0_119:
	s_cmp_gt_u32 s80, 1
	s_cselect_b64 s[84:85], -1, 0
	s_cmp_eq_u32 s73, 3
	s_cselect_b64 s[82:83], -1, 0
	s_waitcnt vmcnt(0) lgkmcnt(0)
	v_pk_mul_f32 v[126:127], v[126:127], v[150:151] op_sel_hi:[1,0]
	v_pk_mul_f32 v[122:123], v[122:123], v[150:151] op_sel_hi:[1,0]
	v_pk_mul_f32 v[128:129], v[128:129], v[150:151] op_sel_hi:[1,0]
	v_pk_mul_f32 v[124:125], v[124:125], v[150:151] op_sel_hi:[1,0]
	s_mov_b64 s[0:1], -1
	s_and_b64 vcc, exec, s[84:85]
	s_cbranch_vccz .LBB0_126
	s_and_b64 vcc, exec, s[6:7]
	s_cbranch_vccz .LBB0_123
	s_andn2_b64 vcc, exec, s[82:83]
	s_cbranch_vccnz .LBB0_328
	v_pk_mul_f32 v[150:151], v[126:127], s[100:101] op_sel_hi:[1,0]
	v_pk_mul_f32 v[152:153], v[128:129], s[100:101] op_sel_hi:[1,0]
	v_pk_mul_f32 v[154:155], v[122:123], s[100:101] op_sel_hi:[1,0]
	v_pk_mul_f32 v[156:157], v[124:125], s[100:101] op_sel_hi:[1,0]
	v_exp_f32_e32 v150, v150
	v_exp_f32_e32 v151, v151
	v_exp_f32_e32 v152, v152
	v_exp_f32_e32 v153, v153
	v_exp_f32_e32 v154, v154
	v_exp_f32_e32 v155, v155
	v_exp_f32_e32 v156, v156
	v_exp_f32_e32 v157, v157
	v_pk_add_f32 v[150:151], v[150:151], s[98:99] op_sel_hi:[1,0]
	v_pk_add_f32 v[152:153], v[152:153], s[98:99] op_sel_hi:[1,0]
	v_pk_add_f32 v[154:155], v[154:155], s[98:99] op_sel_hi:[1,0]
	v_pk_add_f32 v[156:157], v[156:157], s[98:99] op_sel_hi:[1,0]
	v_rcp_f32_e32 v150, v150
	v_rcp_f32_e32 v151, v151
	v_rcp_f32_e32 v152, v152
	v_rcp_f32_e32 v153, v153
	v_rcp_f32_e32 v154, v154
	v_rcp_f32_e32 v155, v155
	v_rcp_f32_e32 v156, v156
	v_rcp_f32_e32 v157, v157
	s_mov_b64 s[0:1], 0
	v_pk_mul_f32 v[150:151], v[126:127], v[150:151]
	v_pk_mul_f32 v[152:153], v[128:129], v[152:153]
	v_pk_mul_f32 v[154:155], v[122:123], v[154:155]
	v_pk_mul_f32 v[156:157], v[124:125], v[156:157]

;     __device__ __forceinline__ void operator()(const f32x4 (&acc)[2][2][4][2], const Unit& u, int wr, int wc, int fr, int fq) const {
;     ...
;                     for (int i = 0; i < 4; ++i) { v[i] = acc[ai][bj][m][0][i] * rs; v[4 + i] = acc[ai][bj][m][1][i] * rs; }
;                     if (seg == 0) {
; #pragma unroll
;                         for (int i = 0; i < 8; ++i) v[i] = v[i] * __builtin_amdgcn_rcpf(1.0f + __expf(-v[i])) * 0.08838834764831845f;
.LBB0_126:
	s_andn2_b64 vcc, exec, s[0:1]
	s_cbranch_vccnz .LBB0_128
	v_pk_mul_f32 v[150:151], v[126:127], s[100:101] op_sel_hi:[1,0]
	v_pk_mul_f32 v[152:153], v[128:129], s[100:101] op_sel_hi:[1,0]
	v_pk_mul_f32 v[154:155], v[122:123], s[100:101] op_sel_hi:[1,0]
	v_pk_mul_f32 v[156:157], v[124:125], s[100:101] op_sel_hi:[1,0]
	v_exp_f32_e32 v150, v150
	v_exp_f32_e32 v151, v151
	v_exp_f32_e32 v152, v152
	v_exp_f32_e32 v153, v153
	v_exp_f32_e32 v154, v154
	v_exp_f32_e32 v155, v155
	v_exp_f32_e32 v156, v156
	v_exp_f32_e32 v157, v157
	v_pk_add_f32 v[150:151], v[150:151], s[98:99] op_sel_hi:[1,0]
	v_pk_add_f32 v[152:153], v[152:153], s[98:99] op_sel_hi:[1,0]
	v_pk_add_f32 v[154:155], v[154:155], s[98:99] op_sel_hi:[1,0]
	v_pk_add_f32 v[156:157], v[156:157], s[98:99] op_sel_hi:[1,0]
	v_rcp_f32_e32 v150, v150
	v_rcp_f32_e32 v151, v151
	v_rcp_f32_e32 v152, v152
	v_rcp_f32_e32 v153, v153
	v_rcp_f32_e32 v154, v154
	v_rcp_f32_e32 v155, v155
	v_rcp_f32_e32 v156, v156
	v_rcp_f32_e32 v157, v157
	s_nop 0
	v_pk_mul_f32 v[126:127], v[126:127], v[150:151]
	v_pk_mul_f32 v[128:129], v[128:129], v[152:153]
	v_pk_mul_f32 v[122:123], v[122:123], v[154:155]
	v_pk_mul_f32 v[124:125], v[124:125], v[156:157]
	v_pk_mul_f32 v[154:155], v[122:123], s[70:71] op_sel_hi:[1,0]
	v_pk_mul_f32 v[156:157], v[124:125], s[70:71] op_sel_hi:[1,0]
	v_pk_mul_f32 v[152:153], v[128:129], s[70:71] op_sel_hi:[1,0]
	v_pk_mul_f32 v[150:151], v[126:127], s[70:71] op_sel_hi:[1,0]

;     __device__ __forceinline__ void operator()(const f32x4 (&acc)[2][2][4][2], const Unit& u, int wr, int wc, int fr, int fq) const {
;     ...
;                     for (int i = 0; i < 4; ++i) { v[i] = acc[ai][bj][m][0][i] * rs; v[4 + i] = acc[ai][bj][m][1][i] * rs; }
;                     if (seg == 0) {
; #pragma unroll
;                         for (int i = 0; i < 8; ++i) v[i] = v[i] * __builtin_amdgcn_rcpf(1.0f + __expf(-v[i])) * 0.08838834764831845f;
;                     } else if (seg == 1) {
; #pragma unroll
;                         for (int i = 0; i < 8; ++i) { const float s = __builtin_amdgcn_rcpf(1.0f + __expf(-v[i])); v[i] = __logf(lb[i] + (1.0f - lb[i]) * s); }
;                     } else if (seg == 3) {
; #pragma unroll
;                         for (int i = 0; i < 8; ++i) v[i] = v[i] * __builtin_amdgcn_rcpf(1.0f + __expf(-v[i]));
.LBB0_132:
	s_waitcnt vmcnt(0) lgkmcnt(0)
	v_pk_mul_f32 v[118:119], v[118:119], v[126:127] op_sel_hi:[1,0]
	v_pk_mul_f32 v[114:115], v[114:115], v[126:127] op_sel_hi:[1,0]
	v_pk_mul_f32 v[120:121], v[120:121], v[126:127] op_sel_hi:[1,0]
	v_pk_mul_f32 v[116:117], v[116:117], v[126:127] op_sel_hi:[1,0]
	v_cndmask_b32_e64 v126, 0, 1, s[84:85]
	v_cmp_ne_u32_e64 s[8:9], 1, v126
	v_cndmask_b32_e64 v126, 0, 1, s[6:7]
	s_mov_b64 s[0:1], -1
	s_andn2_b64 vcc, exec, s[84:85]
	v_cmp_ne_u32_e64 s[6:7], 1, v126
	s_cbranch_vccnz .LBB0_139
	s_and_b64 vcc, exec, s[6:7]
	s_cbranch_vccnz .LBB0_136
	s_andn2_b64 vcc, exec, s[82:83]
	s_cbranch_vccnz .LBB0_329
	v_pk_mul_f32 v[126:127], v[118:119], s[100:101] op_sel_hi:[1,0]
	v_pk_mul_f32 v[128:129], v[120:121], s[100:101] op_sel_hi:[1,0]
	v_pk_mul_f32 v[150:151], v[114:115], s[100:101] op_sel_hi:[1,0]
	v_pk_mul_f32 v[152:153], v[116:117], s[100:101] op_sel_hi:[1,0]
	v_exp_f32_e32 v126, v126
	v_exp_f32_e32 v127, v127
	v_exp_f32_e32 v128, v128
	v_exp_f32_e32 v129, v129
	v_exp_f32_e32 v150, v150
	v_exp_f32_e32 v151, v151
	v_exp_f32_e32 v152, v152
	v_exp_f32_e32 v153, v153
	v_pk_add_f32 v[126:127], v[126:127], s[98:99] op_sel_hi:[1,0]
	v_pk_add_f32 v[128:129], v[128:129], s[98:99] op_sel_hi:[1,0]
	v_pk_add_f32 v[150:151], v[150:151], s[98:99] op_sel_hi:[1,0]
	v_pk_add_f32 v[152:153], v[152:153], s[98:99] op_sel_hi:[1,0]
	v_rcp_f32_e32 v126, v126
	v_rcp_f32_e32 v127, v127
	v_rcp_f32_e32 v128, v128
	v_rcp_f32_e32 v129, v129
	v_rcp_f32_e32 v150, v150
	v_rcp_f32_e32 v151, v151
	v_rcp_f32_e32 v152, v152
	v_rcp_f32_e32 v153, v153
	s_nop 0
	v_pk_mul_f32 v[126:127], v[118:119], v[126:127]
	v_pk_mul_f32 v[128:129], v[120:121], v[128:129]
	v_pk_mul_f32 v[150:151], v[114:115], v[150:151]
	v_pk_mul_f32 v[152:153], v[116:117], v[152:153]
	s_mov_b64 s[0:1], 0

;     __device__ __forceinline__ void operator()(const f32x4 (&acc)[2][2][4][2], const Unit& u, int wr, int wc, int fr, int fq) const {
;     ...
;                     if (seg == 0) {
; #pragma unroll
;                         for (int i = 0; i < 8; ++i) v[i] = v[i] * __builtin_amdgcn_rcpf(1.0f + __expf(-v[i])) * 0.08838834764831845f;
.LBB0_139:
	s_andn2_b64 vcc, exec, s[0:1]
	s_cbranch_vccnz .LBB0_141
	v_pk_mul_f32 v[126:127], v[118:119], s[100:101] op_sel_hi:[1,0]
	v_pk_mul_f32 v[128:129], v[120:121], s[100:101] op_sel_hi:[1,0]
	v_pk_mul_f32 v[150:151], v[114:115], s[100:101] op_sel_hi:[1,0]
	v_pk_mul_f32 v[152:153], v[116:117], s[100:101] op_sel_hi:[1,0]
	v_exp_f32_e32 v126, v126
	v_exp_f32_e32 v127, v127
	v_exp_f32_e32 v128, v128
	v_exp_f32_e32 v129, v129
	v_exp_f32_e32 v150, v150
	v_exp_f32_e32 v151, v151
	v_exp_f32_e32 v152, v152
	v_exp_f32_e32 v153, v153
	v_pk_add_f32 v[126:127], v[126:127], s[98:99] op_sel_hi:[1,0]
	v_pk_add_f32 v[128:129], v[128:129], s[98:99] op_sel_hi:[1,0]
	v_pk_add_f32 v[150:151], v[150:151], s[98:99] op_sel_hi:[1,0]
	v_pk_add_f32 v[152:153], v[152:153], s[98:99] op_sel_hi:[1,0]
	v_rcp_f32_e32 v126, v126
	v_rcp_f32_e32 v127, v127
	v_rcp_f32_e32 v128, v128
	v_rcp_f32_e32 v129, v129
	v_rcp_f32_e32 v150, v150
	v_rcp_f32_e32 v151, v151
	v_rcp_f32_e32 v152, v152
	v_rcp_f32_e32 v153, v153
	s_nop 0
	v_pk_mul_f32 v[118:119], v[118:119], v[126:127]
	v_pk_mul_f32 v[120:121], v[120:121], v[128:129]
	v_pk_mul_f32 v[114:115], v[114:115], v[150:151]
	v_pk_mul_f32 v[116:117], v[116:117], v[152:153]
	v_pk_mul_f32 v[150:151], v[114:115], s[70:71] op_sel_hi:[1,0]
	v_pk_mul_f32 v[152:153], v[116:117], s[70:71] op_sel_hi:[1,0]
	v_pk_mul_f32 v[128:129], v[120:121], s[70:71] op_sel_hi:[1,0]
	v_pk_mul_f32 v[126:127], v[118:119], s[70:71] op_sel_hi:[1,0]

;     __device__ __forceinline__ void operator()(const f32x4 (&acc)[2][2][4][2], const Unit& u, int wr, int wc, int fr, int fq) const {
;     ...
;                     for (int i = 0; i < 4; ++i) { v[i] = acc[ai][bj][m][0][i] * rs; v[4 + i] = acc[ai][bj][m][1][i] * rs; }
;                     if (seg == 0) {
; #pragma unroll
;                         for (int i = 0; i < 8; ++i) v[i] = v[i] * __builtin_amdgcn_rcpf(1.0f + __expf(-v[i])) * 0.08838834764831845f;
;                     } else if (seg == 1) {
; #pragma unroll
;                         for (int i = 0; i < 8; ++i) { const float s = __builtin_amdgcn_rcpf(1.0f + __expf(-v[i])); v[i] = __logf(lb[i] + (1.0f - lb[i]) * s); }
;                     } else if (seg == 3) {
; #pragma unroll
;                         for (int i = 0; i < 8; ++i) v[i] = v[i] * __builtin_amdgcn_rcpf(1.0f + __expf(-v[i]));
.LBB0_145:
	s_waitcnt vmcnt(0) lgkmcnt(0)
	v_pk_mul_f32 v[110:111], v[110:111], v[118:119] op_sel_hi:[1,0]
	v_pk_mul_f32 v[106:107], v[106:107], v[118:119] op_sel_hi:[1,0]
	v_pk_mul_f32 v[112:113], v[112:113], v[118:119] op_sel_hi:[1,0]
	v_pk_mul_f32 v[108:109], v[108:109], v[118:119] op_sel_hi:[1,0]
	s_and_b64 vcc, exec, s[8:9]
	s_mov_b64 s[0:1], -1
	s_cbranch_vccnz .LBB0_152
	s_and_b64 vcc, exec, s[6:7]
	s_cbranch_vccnz .LBB0_149
	s_andn2_b64 vcc, exec, s[82:83]
	s_cbranch_vccnz .LBB0_330
	v_pk_mul_f32 v[118:119], v[110:111], s[100:101] op_sel_hi:[1,0]
	v_pk_mul_f32 v[120:121], v[112:113], s[100:101] op_sel_hi:[1,0]
	v_pk_mul_f32 v[126:127], v[106:107], s[100:101] op_sel_hi:[1,0]
	v_pk_mul_f32 v[128:129], v[108:109], s[100:101] op_sel_hi:[1,0]
	v_exp_f32_e32 v118, v118
	v_exp_f32_e32 v119, v119
	v_exp_f32_e32 v120, v120
	v_exp_f32_e32 v121, v121
	v_exp_f32_e32 v126, v126
	v_exp_f32_e32 v127, v127
	v_exp_f32_e32 v128, v128
	v_exp_f32_e32 v129, v129
	v_pk_add_f32 v[118:119], v[118:119], s[98:99] op_sel_hi:[1,0]
	v_pk_add_f32 v[120:121], v[120:121], s[98:99] op_sel_hi:[1,0]
	v_pk_add_f32 v[126:127], v[126:127], s[98:99] op_sel_hi:[1,0]
	v_pk_add_f32 v[128:129], v[128:129], s[98:99] op_sel_hi:[1,0]
	v_rcp_f32_e32 v118, v118
	v_rcp_f32_e32 v119, v119
	v_rcp_f32_e32 v120, v120
	v_rcp_f32_e32 v121, v121
	v_rcp_f32_e32 v126, v126
	v_rcp_f32_e32 v127, v127
	v_rcp_f32_e32 v128, v128
	v_rcp_f32_e32 v129, v129
	s_nop 0
	v_pk_mul_f32 v[118:119], v[110:111], v[118:119]
	v_pk_mul_f32 v[120:121], v[112:113], v[120:121]
	v_pk_mul_f32 v[126:127], v[106:107], v[126:127]
	v_pk_mul_f32 v[128:129], v[108:109], v[128:129]
	s_mov_b64 s[0:1], 0

;     __device__ __forceinline__ void operator()(const f32x4 (&acc)[2][2][4][2], const Unit& u, int wr, int wc, int fr, int fq) const {
;     ...
;                     if (seg == 0) {
; #pragma unroll
;                         for (int i = 0; i < 8; ++i) v[i] = v[i] * __builtin_amdgcn_rcpf(1.0f + __expf(-v[i])) * 0.08838834764831845f;
.LBB0_152:
	s_andn2_b64 vcc, exec, s[0:1]
	s_cbranch_vccnz .LBB0_154
	v_pk_mul_f32 v[118:119], v[110:111], s[100:101] op_sel_hi:[1,0]
	v_pk_mul_f32 v[120:121], v[112:113], s[100:101] op_sel_hi:[1,0]
	v_pk_mul_f32 v[126:127], v[106:107], s[100:101] op_sel_hi:[1,0]
	v_pk_mul_f32 v[128:129], v[108:109], s[100:101] op_sel_hi:[1,0]
	v_exp_f32_e32 v118, v118
	v_exp_f32_e32 v119, v119
	v_exp_f32_e32 v120, v120
	v_exp_f32_e32 v121, v121
	v_exp_f32_e32 v126, v126
	v_exp_f32_e32 v127, v127
	v_exp_f32_e32 v128, v128
	v_exp_f32_e32 v129, v129
	v_pk_add_f32 v[118:119], v[118:119], s[98:99] op_sel_hi:[1,0]
	v_pk_add_f32 v[120:121], v[120:121], s[98:99] op_sel_hi:[1,0]
	v_pk_add_f32 v[126:127], v[126:127], s[98:99] op_sel_hi:[1,0]
	v_pk_add_f32 v[128:129], v[128:129], s[98:99] op_sel_hi:[1,0]
	v_rcp_f32_e32 v118, v118
	v_rcp_f32_e32 v119, v119
	v_rcp_f32_e32 v120, v120
	v_rcp_f32_e32 v121, v121
	v_rcp_f32_e32 v126, v126
	v_rcp_f32_e32 v127, v127
	v_rcp_f32_e32 v128, v128
	v_rcp_f32_e32 v129, v129
	s_nop 0
	v_pk_mul_f32 v[110:111], v[110:111], v[118:119]
	v_pk_mul_f32 v[112:113], v[112:113], v[120:121]
	v_pk_mul_f32 v[106:107], v[106:107], v[126:127]
	v_pk_mul_f32 v[108:109], v[108:109], v[128:129]
	v_pk_mul_f32 v[126:127], v[106:107], s[70:71] op_sel_hi:[1,0]
	v_pk_mul_f32 v[128:129], v[108:109], s[70:71] op_sel_hi:[1,0]
	v_pk_mul_f32 v[120:121], v[112:113], s[70:71] op_sel_hi:[1,0]
	v_pk_mul_f32 v[118:119], v[110:111], s[70:71] op_sel_hi:[1,0]

;     __device__ __forceinline__ void operator()(const f32x4 (&acc)[2][2][4][2], const Unit& u, int wr, int wc, int fr, int fq) const {
;     ...
;                     for (int i = 0; i < 4; ++i) { v[i] = acc[ai][bj][m][0][i] * rs; v[4 + i] = acc[ai][bj][m][1][i] * rs; }
;                     if (seg == 0) {
; #pragma unroll
;                         for (int i = 0; i < 8; ++i) v[i] = v[i] * __builtin_amdgcn_rcpf(1.0f + __expf(-v[i])) * 0.08838834764831845f;
;                     } else if (seg == 1) {
; #pragma unroll
;                         for (int i = 0; i < 8; ++i) { const float s = __builtin_amdgcn_rcpf(1.0f + __expf(-v[i])); v[i] = __logf(lb[i] + (1.0f - lb[i]) * s); }
;                     } else if (seg == 3) {
; #pragma unroll
;                         for (int i = 0; i < 8; ++i) v[i] = v[i] * __builtin_amdgcn_rcpf(1.0f + __expf(-v[i]));
.LBB0_158:
	s_waitcnt vmcnt(0) lgkmcnt(0)
	v_pk_mul_f32 v[102:103], v[102:103], v[110:111] op_sel_hi:[1,0]
	v_pk_mul_f32 v[98:99], v[98:99], v[110:111] op_sel_hi:[1,0]
	v_pk_mul_f32 v[104:105], v[104:105], v[110:111] op_sel_hi:[1,0]
	v_pk_mul_f32 v[100:101], v[100:101], v[110:111] op_sel_hi:[1,0]
	s_and_b64 vcc, exec, s[8:9]
	s_mov_b64 s[0:1], -1
	s_cbranch_vccnz .LBB0_165
	s_and_b64 vcc, exec, s[6:7]
	s_cbranch_vccnz .LBB0_162
	s_andn2_b64 vcc, exec, s[82:83]
	s_cbranch_vccnz .LBB0_331
	v_pk_mul_f32 v[110:111], v[102:103], s[100:101] op_sel_hi:[1,0]
	v_pk_mul_f32 v[112:113], v[104:105], s[100:101] op_sel_hi:[1,0]
	v_pk_mul_f32 v[118:119], v[98:99], s[100:101] op_sel_hi:[1,0]
	v_pk_mul_f32 v[120:121], v[100:101], s[100:101] op_sel_hi:[1,0]
	v_exp_f32_e32 v110, v110
	v_exp_f32_e32 v111, v111
	v_exp_f32_e32 v112, v112
	v_exp_f32_e32 v113, v113
	v_exp_f32_e32 v118, v118
	v_exp_f32_e32 v119, v119
	v_exp_f32_e32 v120, v120
	v_exp_f32_e32 v121, v121
	v_pk_add_f32 v[110:111], v[110:111], s[98:99] op_sel_hi:[1,0]
	v_pk_add_f32 v[112:113], v[112:113], s[98:99] op_sel_hi:[1,0]
	v_pk_add_f32 v[118:119], v[118:119], s[98:99] op_sel_hi:[1,0]
	v_pk_add_f32 v[120:121], v[120:121], s[98:99] op_sel_hi:[1,0]
	v_rcp_f32_e32 v110, v110
	v_rcp_f32_e32 v111, v111
	v_rcp_f32_e32 v112, v112
	v_rcp_f32_e32 v113, v113
	v_rcp_f32_e32 v118, v118
	v_rcp_f32_e32 v119, v119
	v_rcp_f32_e32 v120, v120
	v_rcp_f32_e32 v121, v121
	s_nop 0
	v_pk_mul_f32 v[110:111], v[102:103], v[110:111]
	v_pk_mul_f32 v[112:113], v[104:105], v[112:113]
	v_pk_mul_f32 v[118:119], v[98:99], v[118:119]
	v_pk_mul_f32 v[120:121], v[100:101], v[120:121]
	s_mov_b64 s[0:1], 0

;     __device__ __forceinline__ void operator()(const f32x4 (&acc)[2][2][4][2], const Unit& u, int wr, int wc, int fr, int fq) const {
;     ...
;                     if (seg == 0) {
; #pragma unroll
;                         for (int i = 0; i < 8; ++i) v[i] = v[i] * __builtin_amdgcn_rcpf(1.0f + __expf(-v[i])) * 0.08838834764831845f;
.LBB0_165:
	s_andn2_b64 vcc, exec, s[0:1]
	s_cbranch_vccnz .LBB0_167
	v_pk_mul_f32 v[110:111], v[102:103], s[100:101] op_sel_hi:[1,0]
	v_pk_mul_f32 v[112:113], v[104:105], s[100:101] op_sel_hi:[1,0]
	v_pk_mul_f32 v[118:119], v[98:99], s[100:101] op_sel_hi:[1,0]
	v_pk_mul_f32 v[120:121], v[100:101], s[100:101] op_sel_hi:[1,0]
	v_exp_f32_e32 v110, v110
	v_exp_f32_e32 v111, v111
	v_exp_f32_e32 v112, v112
	v_exp_f32_e32 v113, v113
	v_exp_f32_e32 v118, v118
	v_exp_f32_e32 v119, v119
	v_exp_f32_e32 v120, v120
	v_exp_f32_e32 v121, v121
	v_pk_add_f32 v[110:111], v[110:111], s[98:99] op_sel_hi:[1,0]
	v_pk_add_f32 v[112:113], v[112:113], s[98:99] op_sel_hi:[1,0]
	v_pk_add_f32 v[118:119], v[118:119], s[98:99] op_sel_hi:[1,0]
	v_pk_add_f32 v[120:121], v[120:121], s[98:99] op_sel_hi:[1,0]
	v_rcp_f32_e32 v110, v110
	v_rcp_f32_e32 v111, v111
	v_rcp_f32_e32 v112, v112
	v_rcp_f32_e32 v113, v113
	v_rcp_f32_e32 v118, v118
	v_rcp_f32_e32 v119, v119
	v_rcp_f32_e32 v120, v120
	v_rcp_f32_e32 v121, v121
	s_nop 0
	v_pk_mul_f32 v[102:103], v[102:103], v[110:111]
	v_pk_mul_f32 v[104:105], v[104:105], v[112:113]
	v_pk_mul_f32 v[98:99], v[98:99], v[118:119]
	v_pk_mul_f32 v[100:101], v[100:101], v[120:121]
	v_pk_mul_f32 v[118:119], v[98:99], s[70:71] op_sel_hi:[1,0]
	v_pk_mul_f32 v[120:121], v[100:101], s[70:71] op_sel_hi:[1,0]
	v_pk_mul_f32 v[112:113], v[104:105], s[70:71] op_sel_hi:[1,0]
	v_pk_mul_f32 v[110:111], v[102:103], s[70:71] op_sel_hi:[1,0]

;     __device__ __forceinline__ void operator()(const f32x4 (&acc)[2][2][4][2], const Unit& u, int wr, int wc, int fr, int fq) const {
;     ...
;                     for (int i = 0; i < 4; ++i) { v[i] = acc[ai][bj][m][0][i] * rs; v[4 + i] = acc[ai][bj][m][1][i] * rs; }
;                     if (seg == 0) {
; #pragma unroll
;                         for (int i = 0; i < 8; ++i) v[i] = v[i] * __builtin_amdgcn_rcpf(1.0f + __expf(-v[i])) * 0.08838834764831845f;
;                     } else if (seg == 1) {
; #pragma unroll
;                         for (int i = 0; i < 8; ++i) { const float s = __builtin_amdgcn_rcpf(1.0f + __expf(-v[i])); v[i] = __logf(lb[i] + (1.0f - lb[i]) * s); }
;                     } else if (seg == 3) {
; #pragma unroll
;                         for (int i = 0; i < 8; ++i) v[i] = v[i] * __builtin_amdgcn_rcpf(1.0f + __expf(-v[i]));
.LBB0_171:
	s_waitcnt vmcnt(0) lgkmcnt(0)
	v_pk_mul_f32 v[94:95], v[94:95], v[102:103] op_sel_hi:[1,0]
	v_pk_mul_f32 v[90:91], v[90:91], v[102:103] op_sel_hi:[1,0]
	v_pk_mul_f32 v[96:97], v[96:97], v[102:103] op_sel_hi:[1,0]
	v_pk_mul_f32 v[92:93], v[92:93], v[102:103] op_sel_hi:[1,0]
	s_and_b64 vcc, exec, s[8:9]
	s_mov_b64 s[0:1], -1
	s_cbranch_vccnz .LBB0_178
	s_and_b64 vcc, exec, s[6:7]
	s_cbranch_vccnz .LBB0_175
	s_andn2_b64 vcc, exec, s[82:83]
	s_cbranch_vccnz .LBB0_332
	v_pk_mul_f32 v[102:103], v[94:95], s[100:101] op_sel_hi:[1,0]
	v_pk_mul_f32 v[104:105], v[96:97], s[100:101] op_sel_hi:[1,0]
	v_pk_mul_f32 v[110:111], v[90:91], s[100:101] op_sel_hi:[1,0]
	v_pk_mul_f32 v[112:113], v[92:93], s[100:101] op_sel_hi:[1,0]
	v_exp_f32_e32 v102, v102
	v_exp_f32_e32 v103, v103
	v_exp_f32_e32 v104, v104
	v_exp_f32_e32 v105, v105
	v_exp_f32_e32 v110, v110
	v_exp_f32_e32 v111, v111
	v_exp_f32_e32 v112, v112
	v_exp_f32_e32 v113, v113
	v_pk_add_f32 v[102:103], v[102:103], s[98:99] op_sel_hi:[1,0]
	v_pk_add_f32 v[104:105], v[104:105], s[98:99] op_sel_hi:[1,0]
	v_pk_add_f32 v[110:111], v[110:111], s[98:99] op_sel_hi:[1,0]
	v_pk_add_f32 v[112:113], v[112:113], s[98:99] op_sel_hi:[1,0]
	v_rcp_f32_e32 v102, v102
	v_rcp_f32_e32 v103, v103
	v_rcp_f32_e32 v104, v104
	v_rcp_f32_e32 v105, v105
	v_rcp_f32_e32 v110, v110
	v_rcp_f32_e32 v111, v111
	v_rcp_f32_e32 v112, v112
	v_rcp_f32_e32 v113, v113
	s_nop 0
	v_pk_mul_f32 v[102:103], v[94:95], v[102:103]
	v_pk_mul_f32 v[104:105], v[96:97], v[104:105]
	v_pk_mul_f32 v[110:111], v[90:91], v[110:111]
	v_pk_mul_f32 v[112:113], v[92:93], v[112:113]
	s_mov_b64 s[0:1], 0

;     __device__ __forceinline__ void operator()(const f32x4 (&acc)[2][2][4][2], const Unit& u, int wr, int wc, int fr, int fq) const {
;     ...
;                     if (seg == 0) {
; #pragma unroll
;                         for (int i = 0; i < 8; ++i) v[i] = v[i] * __builtin_amdgcn_rcpf(1.0f + __expf(-v[i])) * 0.08838834764831845f;
.LBB0_178:
	s_andn2_b64 vcc, exec, s[0:1]
	s_cbranch_vccnz .LBB0_180
	v_pk_mul_f32 v[102:103], v[94:95], s[100:101] op_sel_hi:[1,0]
	v_pk_mul_f32 v[104:105], v[96:97], s[100:101] op_sel_hi:[1,0]
	v_pk_mul_f32 v[110:111], v[90:91], s[100:101] op_sel_hi:[1,0]
	v_pk_mul_f32 v[112:113], v[92:93], s[100:101] op_sel_hi:[1,0]
	v_exp_f32_e32 v102, v102
	v_exp_f32_e32 v103, v103
	v_exp_f32_e32 v104, v104
	v_exp_f32_e32 v105, v105
	v_exp_f32_e32 v110, v110
	v_exp_f32_e32 v111, v111
	v_exp_f32_e32 v112, v112
	v_exp_f32_e32 v113, v113
	v_pk_add_f32 v[102:103], v[102:103], s[98:99] op_sel_hi:[1,0]
	v_pk_add_f32 v[104:105], v[104:105], s[98:99] op_sel_hi:[1,0]
	v_pk_add_f32 v[110:111], v[110:111], s[98:99] op_sel_hi:[1,0]
	v_pk_add_f32 v[112:113], v[112:113], s[98:99] op_sel_hi:[1,0]
	v_rcp_f32_e32 v102, v102
	v_rcp_f32_e32 v103, v103
	v_rcp_f32_e32 v104, v104
	v_rcp_f32_e32 v105, v105
	v_rcp_f32_e32 v110, v110
	v_rcp_f32_e32 v111, v111
	v_rcp_f32_e32 v112, v112
	v_rcp_f32_e32 v113, v113
	s_nop 0
	v_pk_mul_f32 v[94:95], v[94:95], v[102:103]
	v_pk_mul_f32 v[96:97], v[96:97], v[104:105]
	v_pk_mul_f32 v[90:91], v[90:91], v[110:111]
	v_pk_mul_f32 v[92:93], v[92:93], v[112:113]
	v_pk_mul_f32 v[110:111], v[90:91], s[70:71] op_sel_hi:[1,0]
	v_pk_mul_f32 v[112:113], v[92:93], s[70:71] op_sel_hi:[1,0]
	v_pk_mul_f32 v[104:105], v[96:97], s[70:71] op_sel_hi:[1,0]
	v_pk_mul_f32 v[102:103], v[94:95], s[70:71] op_sel_hi:[1,0]

;     __device__ __forceinline__ void operator()(const f32x4 (&acc)[2][2][4][2], const Unit& u, int wr, int wc, int fr, int fq) const {
;     ...
;                     for (int i = 0; i < 4; ++i) { v[i] = acc[ai][bj][m][0][i] * rs; v[4 + i] = acc[ai][bj][m][1][i] * rs; }
;                     if (seg == 0) {
; #pragma unroll
;                         for (int i = 0; i < 8; ++i) v[i] = v[i] * __builtin_amdgcn_rcpf(1.0f + __expf(-v[i])) * 0.08838834764831845f;
;                     } else if (seg == 1) {
; #pragma unroll
;                         for (int i = 0; i < 8; ++i) { const float s = __builtin_amdgcn_rcpf(1.0f + __expf(-v[i])); v[i] = __logf(lb[i] + (1.0f - lb[i]) * s); }
;                     } else if (seg == 3) {
; #pragma unroll
;                         for (int i = 0; i < 8; ++i) v[i] = v[i] * __builtin_amdgcn_rcpf(1.0f + __expf(-v[i]));
.LBB0_184:
	s_waitcnt vmcnt(0) lgkmcnt(0)
	v_pk_mul_f32 v[86:87], v[86:87], v[94:95] op_sel_hi:[1,0]
	v_pk_mul_f32 v[82:83], v[82:83], v[94:95] op_sel_hi:[1,0]
	v_pk_mul_f32 v[88:89], v[88:89], v[94:95] op_sel_hi:[1,0]
	v_pk_mul_f32 v[84:85], v[84:85], v[94:95] op_sel_hi:[1,0]
	s_and_b64 vcc, exec, s[8:9]
	s_mov_b64 s[0:1], -1
	s_cbranch_vccnz .LBB0_191
	s_and_b64 vcc, exec, s[6:7]
	s_cbranch_vccnz .LBB0_188
	s_andn2_b64 vcc, exec, s[82:83]
	s_cbranch_vccnz .LBB0_333
	v_pk_mul_f32 v[94:95], v[86:87], s[100:101] op_sel_hi:[1,0]
	v_pk_mul_f32 v[96:97], v[88:89], s[100:101] op_sel_hi:[1,0]
	v_pk_mul_f32 v[102:103], v[82:83], s[100:101] op_sel_hi:[1,0]
	v_pk_mul_f32 v[104:105], v[84:85], s[100:101] op_sel_hi:[1,0]
	v_exp_f32_e32 v94, v94
	v_exp_f32_e32 v95, v95
	v_exp_f32_e32 v96, v96
	v_exp_f32_e32 v97, v97
	v_exp_f32_e32 v102, v102
	v_exp_f32_e32 v103, v103
	v_exp_f32_e32 v104, v104
	v_exp_f32_e32 v105, v105
	v_pk_add_f32 v[94:95], v[94:95], s[98:99] op_sel_hi:[1,0]
	v_pk_add_f32 v[96:97], v[96:97], s[98:99] op_sel_hi:[1,0]
	v_pk_add_f32 v[102:103], v[102:103], s[98:99] op_sel_hi:[1,0]
	v_pk_add_f32 v[104:105], v[104:105], s[98:99] op_sel_hi:[1,0]
	v_rcp_f32_e32 v94, v94
	v_rcp_f32_e32 v95, v95
	v_rcp_f32_e32 v96, v96
	v_rcp_f32_e32 v97, v97
	v_rcp_f32_e32 v102, v102
	v_rcp_f32_e32 v103, v103
	v_rcp_f32_e32 v104, v104
	v_rcp_f32_e32 v105, v105
	s_nop 0
	v_pk_mul_f32 v[94:95], v[86:87], v[94:95]
	v_pk_mul_f32 v[96:97], v[88:89], v[96:97]
	v_pk_mul_f32 v[102:103], v[82:83], v[102:103]
	v_pk_mul_f32 v[104:105], v[84:85], v[104:105]
	s_mov_b64 s[0:1], 0

;     __device__ __forceinline__ void operator()(const f32x4 (&acc)[2][2][4][2], const Unit& u, int wr, int wc, int fr, int fq) const {
;     ...
;                     if (seg == 0) {
; #pragma unroll
;                         for (int i = 0; i < 8; ++i) v[i] = v[i] * __builtin_amdgcn_rcpf(1.0f + __expf(-v[i])) * 0.08838834764831845f;
.LBB0_191:
	s_andn2_b64 vcc, exec, s[0:1]
	s_cbranch_vccnz .LBB0_193
	v_pk_mul_f32 v[94:95], v[86:87], s[100:101] op_sel_hi:[1,0]
	v_pk_mul_f32 v[96:97], v[88:89], s[100:101] op_sel_hi:[1,0]
	v_pk_mul_f32 v[102:103], v[82:83], s[100:101] op_sel_hi:[1,0]
	v_pk_mul_f32 v[104:105], v[84:85], s[100:101] op_sel_hi:[1,0]
	v_exp_f32_e32 v94, v94
	v_exp_f32_e32 v95, v95
	v_exp_f32_e32 v96, v96
	v_exp_f32_e32 v97, v97
	v_exp_f32_e32 v102, v102
	v_exp_f32_e32 v103, v103
	v_exp_f32_e32 v104, v104
	v_exp_f32_e32 v105, v105
	v_pk_add_f32 v[94:95], v[94:95], s[98:99] op_sel_hi:[1,0]
	v_pk_add_f32 v[96:97], v[96:97], s[98:99] op_sel_hi:[1,0]
	v_pk_add_f32 v[102:103], v[102:103], s[98:99] op_sel_hi:[1,0]
	v_pk_add_f32 v[104:105], v[104:105], s[98:99] op_sel_hi:[1,0]
	v_rcp_f32_e32 v94, v94
	v_rcp_f32_e32 v95, v95
	v_rcp_f32_e32 v96, v96
	v_rcp_f32_e32 v97, v97
	v_rcp_f32_e32 v102, v102
	v_rcp_f32_e32 v103, v103
	v_rcp_f32_e32 v104, v104
	v_rcp_f32_e32 v105, v105
	s_nop 0
	v_pk_mul_f32 v[86:87], v[86:87], v[94:95]
	v_pk_mul_f32 v[88:89], v[88:89], v[96:97]
	v_pk_mul_f32 v[82:83], v[82:83], v[102:103]
	v_pk_mul_f32 v[84:85], v[84:85], v[104:105]
	v_pk_mul_f32 v[102:103], v[82:83], s[70:71] op_sel_hi:[1,0]
	v_pk_mul_f32 v[104:105], v[84:85], s[70:71] op_sel_hi:[1,0]
	v_pk_mul_f32 v[96:97], v[88:89], s[70:71] op_sel_hi:[1,0]
	v_pk_mul_f32 v[94:95], v[86:87], s[70:71] op_sel_hi:[1,0]

;     __device__ __forceinline__ void operator()(const f32x4 (&acc)[2][2][4][2], const Unit& u, int wr, int wc, int fr, int fq) const {
;     ...
;                     for (int i = 0; i < 4; ++i) { v[i] = acc[ai][bj][m][0][i] * rs; v[4 + i] = acc[ai][bj][m][1][i] * rs; }
;                     if (seg == 0) {
; #pragma unroll
;                         for (int i = 0; i < 8; ++i) v[i] = v[i] * __builtin_amdgcn_rcpf(1.0f + __expf(-v[i])) * 0.08838834764831845f;
;                     } else if (seg == 1) {
; #pragma unroll
;                         for (int i = 0; i < 8; ++i) { const float s = __builtin_amdgcn_rcpf(1.0f + __expf(-v[i])); v[i] = __logf(lb[i] + (1.0f - lb[i]) * s); }
;                     } else if (seg == 3) {
; #pragma unroll
;                         for (int i = 0; i < 8; ++i) v[i] = v[i] * __builtin_amdgcn_rcpf(1.0f + __expf(-v[i]));
.LBB0_197:
	s_waitcnt vmcnt(0) lgkmcnt(0)
	v_pk_mul_f32 v[78:79], v[78:79], v[86:87] op_sel_hi:[1,0]
	v_pk_mul_f32 v[74:75], v[74:75], v[86:87] op_sel_hi:[1,0]
	v_pk_mul_f32 v[80:81], v[80:81], v[86:87] op_sel_hi:[1,0]
	v_pk_mul_f32 v[76:77], v[76:77], v[86:87] op_sel_hi:[1,0]
	s_and_b64 vcc, exec, s[8:9]
	s_mov_b64 s[0:1], -1
	s_cbranch_vccnz .LBB0_204
	s_and_b64 vcc, exec, s[6:7]
	s_cbranch_vccnz .LBB0_201
	s_andn2_b64 vcc, exec, s[82:83]
	s_cbranch_vccnz .LBB0_334
	v_pk_mul_f32 v[86:87], v[78:79], s[100:101] op_sel_hi:[1,0]
	v_pk_mul_f32 v[88:89], v[80:81], s[100:101] op_sel_hi:[1,0]
	v_pk_mul_f32 v[94:95], v[74:75], s[100:101] op_sel_hi:[1,0]
	v_pk_mul_f32 v[96:97], v[76:77], s[100:101] op_sel_hi:[1,0]
	v_exp_f32_e32 v86, v86
	v_exp_f32_e32 v87, v87
	v_exp_f32_e32 v88, v88
	v_exp_f32_e32 v89, v89
	v_exp_f32_e32 v94, v94
	v_exp_f32_e32 v95, v95
	v_exp_f32_e32 v96, v96
	v_exp_f32_e32 v97, v97
	v_pk_add_f32 v[86:87], v[86:87], s[98:99] op_sel_hi:[1,0]
	v_pk_add_f32 v[88:89], v[88:89], s[98:99] op_sel_hi:[1,0]
	v_pk_add_f32 v[94:95], v[94:95], s[98:99] op_sel_hi:[1,0]
	v_pk_add_f32 v[96:97], v[96:97], s[98:99] op_sel_hi:[1,0]
	v_rcp_f32_e32 v86, v86
	v_rcp_f32_e32 v87, v87
	v_rcp_f32_e32 v88, v88
	v_rcp_f32_e32 v89, v89
	v_rcp_f32_e32 v94, v94
	v_rcp_f32_e32 v95, v95
	v_rcp_f32_e32 v96, v96
	v_rcp_f32_e32 v97, v97
	s_nop 0
	v_pk_mul_f32 v[86:87], v[78:79], v[86:87]
	v_pk_mul_f32 v[88:89], v[80:81], v[88:89]
	v_pk_mul_f32 v[94:95], v[74:75], v[94:95]
	v_pk_mul_f32 v[96:97], v[76:77], v[96:97]
	s_mov_b64 s[0:1], 0

;     __device__ __forceinline__ void operator()(const f32x4 (&acc)[2][2][4][2], const Unit& u, int wr, int wc, int fr, int fq) const {
;     ...
;                     if (seg == 0) {
; #pragma unroll
;                         for (int i = 0; i < 8; ++i) v[i] = v[i] * __builtin_amdgcn_rcpf(1.0f + __expf(-v[i])) * 0.08838834764831845f;
.LBB0_204:
	s_andn2_b64 vcc, exec, s[0:1]
	s_cbranch_vccnz .LBB0_206
	v_pk_mul_f32 v[86:87], v[78:79], s[100:101] op_sel_hi:[1,0]
	v_pk_mul_f32 v[88:89], v[80:81], s[100:101] op_sel_hi:[1,0]
	v_pk_mul_f32 v[94:95], v[74:75], s[100:101] op_sel_hi:[1,0]
	v_pk_mul_f32 v[96:97], v[76:77], s[100:101] op_sel_hi:[1,0]
	v_exp_f32_e32 v86, v86
	v_exp_f32_e32 v87, v87
	v_exp_f32_e32 v88, v88
	v_exp_f32_e32 v89, v89
	v_exp_f32_e32 v94, v94
	v_exp_f32_e32 v95, v95
	v_exp_f32_e32 v96, v96
	v_exp_f32_e32 v97, v97
	v_pk_add_f32 v[86:87], v[86:87], s[98:99] op_sel_hi:[1,0]
	v_pk_add_f32 v[88:89], v[88:89], s[98:99] op_sel_hi:[1,0]
	v_pk_add_f32 v[94:95], v[94:95], s[98:99] op_sel_hi:[1,0]
	v_pk_add_f32 v[96:97], v[96:97], s[98:99] op_sel_hi:[1,0]
	v_rcp_f32_e32 v86, v86
	v_rcp_f32_e32 v87, v87
	v_rcp_f32_e32 v88, v88
	v_rcp_f32_e32 v89, v89
	v_rcp_f32_e32 v94, v94
	v_rcp_f32_e32 v95, v95
	v_rcp_f32_e32 v96, v96
	v_rcp_f32_e32 v97, v97
	s_nop 0
	v_pk_mul_f32 v[78:79], v[78:79], v[86:87]
	v_pk_mul_f32 v[80:81], v[80:81], v[88:89]
	v_pk_mul_f32 v[74:75], v[74:75], v[94:95]
	v_pk_mul_f32 v[76:77], v[76:77], v[96:97]
	v_pk_mul_f32 v[94:95], v[74:75], s[70:71] op_sel_hi:[1,0]
	v_pk_mul_f32 v[96:97], v[76:77], s[70:71] op_sel_hi:[1,0]
	v_pk_mul_f32 v[88:89], v[80:81], s[70:71] op_sel_hi:[1,0]
	v_pk_mul_f32 v[86:87], v[78:79], s[70:71] op_sel_hi:[1,0]

;     __device__ __forceinline__ void operator()(const f32x4 (&acc)[2][2][4][2], const Unit& u, int wr, int wc, int fr, int fq) const {
;     ...
;                     for (int i = 0; i < 4; ++i) { v[i] = acc[ai][bj][m][0][i] * rs; v[4 + i] = acc[ai][bj][m][1][i] * rs; }
;                     if (seg == 0) {
; #pragma unroll
;                         for (int i = 0; i < 8; ++i) v[i] = v[i] * __builtin_amdgcn_rcpf(1.0f + __expf(-v[i])) * 0.08838834764831845f;
;                     } else if (seg == 1) {
; #pragma unroll
;                         for (int i = 0; i < 8; ++i) { const float s = __builtin_amdgcn_rcpf(1.0f + __expf(-v[i])); v[i] = __logf(lb[i] + (1.0f - lb[i]) * s); }
;                     } else if (seg == 3) {
; #pragma unroll
;                         for (int i = 0; i < 8; ++i) v[i] = v[i] * __builtin_amdgcn_rcpf(1.0f + __expf(-v[i]));
.LBB0_210:
	s_waitcnt vmcnt(0) lgkmcnt(0)
	v_pk_mul_f32 v[70:71], v[70:71], v[78:79] op_sel_hi:[1,0]
	v_pk_mul_f32 v[66:67], v[66:67], v[78:79] op_sel_hi:[1,0]
	v_pk_mul_f32 v[72:73], v[72:73], v[78:79] op_sel_hi:[1,0]
	v_pk_mul_f32 v[68:69], v[68:69], v[78:79] op_sel_hi:[1,0]
	s_and_b64 vcc, exec, s[8:9]
	s_mov_b64 s[0:1], -1
	s_cbranch_vccnz .LBB0_217
	s_and_b64 vcc, exec, s[6:7]
	s_cbranch_vccnz .LBB0_214
	s_andn2_b64 vcc, exec, s[82:83]
	s_cbranch_vccnz .LBB0_335
	v_pk_mul_f32 v[78:79], v[70:71], s[100:101] op_sel_hi:[1,0]
	v_pk_mul_f32 v[80:81], v[72:73], s[100:101] op_sel_hi:[1,0]
	v_pk_mul_f32 v[86:87], v[66:67], s[100:101] op_sel_hi:[1,0]
	v_pk_mul_f32 v[88:89], v[68:69], s[100:101] op_sel_hi:[1,0]
	v_exp_f32_e32 v78, v78
	v_exp_f32_e32 v79, v79
	v_exp_f32_e32 v80, v80
	v_exp_f32_e32 v81, v81
	v_exp_f32_e32 v86, v86
	v_exp_f32_e32 v87, v87
	v_exp_f32_e32 v88, v88
	v_exp_f32_e32 v89, v89
	v_pk_add_f32 v[78:79], v[78:79], s[98:99] op_sel_hi:[1,0]
	v_pk_add_f32 v[80:81], v[80:81], s[98:99] op_sel_hi:[1,0]
	v_pk_add_f32 v[86:87], v[86:87], s[98:99] op_sel_hi:[1,0]
	v_pk_add_f32 v[88:89], v[88:89], s[98:99] op_sel_hi:[1,0]
	v_rcp_f32_e32 v78, v78
	v_rcp_f32_e32 v79, v79
	v_rcp_f32_e32 v80, v80
	v_rcp_f32_e32 v81, v81
	v_rcp_f32_e32 v86, v86
	v_rcp_f32_e32 v87, v87
	v_rcp_f32_e32 v88, v88
	v_rcp_f32_e32 v89, v89
	s_nop 0
	v_pk_mul_f32 v[78:79], v[70:71], v[78:79]
	v_pk_mul_f32 v[80:81], v[72:73], v[80:81]
	v_pk_mul_f32 v[86:87], v[66:67], v[86:87]
	v_pk_mul_f32 v[88:89], v[68:69], v[88:89]
	s_mov_b64 s[0:1], 0

;     __device__ __forceinline__ void operator()(const f32x4 (&acc)[2][2][4][2], const Unit& u, int wr, int wc, int fr, int fq) const {
;     ...
;                     if (seg == 0) {
; #pragma unroll
;                         for (int i = 0; i < 8; ++i) v[i] = v[i] * __builtin_amdgcn_rcpf(1.0f + __expf(-v[i])) * 0.08838834764831845f;
.LBB0_217:
	s_andn2_b64 vcc, exec, s[0:1]
	s_cbranch_vccnz .LBB0_219
	v_pk_mul_f32 v[78:79], v[70:71], s[100:101] op_sel_hi:[1,0]
	v_pk_mul_f32 v[80:81], v[72:73], s[100:101] op_sel_hi:[1,0]
	v_pk_mul_f32 v[86:87], v[66:67], s[100:101] op_sel_hi:[1,0]
	v_pk_mul_f32 v[88:89], v[68:69], s[100:101] op_sel_hi:[1,0]
	v_exp_f32_e32 v78, v78
	v_exp_f32_e32 v79, v79
	v_exp_f32_e32 v80, v80
	v_exp_f32_e32 v81, v81
	v_exp_f32_e32 v86, v86
	v_exp_f32_e32 v87, v87
	v_exp_f32_e32 v88, v88
	v_exp_f32_e32 v89, v89
	v_pk_add_f32 v[78:79], v[78:79], s[98:99] op_sel_hi:[1,0]
	v_pk_add_f32 v[80:81], v[80:81], s[98:99] op_sel_hi:[1,0]
	v_pk_add_f32 v[86:87], v[86:87], s[98:99] op_sel_hi:[1,0]
	v_pk_add_f32 v[88:89], v[88:89], s[98:99] op_sel_hi:[1,0]
	v_rcp_f32_e32 v78, v78
	v_rcp_f32_e32 v79, v79
	v_rcp_f32_e32 v80, v80
	v_rcp_f32_e32 v81, v81
	v_rcp_f32_e32 v86, v86
	v_rcp_f32_e32 v87, v87
	v_rcp_f32_e32 v88, v88
	v_rcp_f32_e32 v89, v89
	s_nop 0
	v_pk_mul_f32 v[70:71], v[70:71], v[78:79]
	v_pk_mul_f32 v[72:73], v[72:73], v[80:81]
	v_pk_mul_f32 v[66:67], v[66:67], v[86:87]
	v_pk_mul_f32 v[68:69], v[68:69], v[88:89]
	v_pk_mul_f32 v[86:87], v[66:67], s[70:71] op_sel_hi:[1,0]
	v_pk_mul_f32 v[88:89], v[68:69], s[70:71] op_sel_hi:[1,0]
	v_pk_mul_f32 v[80:81], v[72:73], s[70:71] op_sel_hi:[1,0]
	v_pk_mul_f32 v[78:79], v[70:71], s[70:71] op_sel_hi:[1,0]

;     __device__ __forceinline__ void operator()(const f32x4 (&acc)[2][2][4][2], const Unit& u, int wr, int wc, int fr, int fq) const {
;     ...
;             const int col0 = u.pn * BM + bj * HALF + wc * 32 + 8 * fq;
;             const int seg = __builtin_amdgcn_readfirstlane(col0 >> 9);
;             float lb[8];
; #pragma unroll
;             for (int i = 0; i < 8; ++i) lb[i] = 0.f;
;             if (seg == 1) {
;                 const int ci = col0 & 511;
; #pragma unroll
;                 for (int i = 0; i < 8; ++i) { const float l0 = lbl[ci + i], l1 = lbl[512 + ci + i]; lb[i] = __builtin_amdgcn_rcpf(1.0f + __expf(l1 - l0)); }
;             }
; #pragma unroll
;             for (int ai = 0; ai < 2; ++ai)
; #pragma unroll
;                 for (int m = 0; m < 4; ++m) {
;                     const int row = row0 + ai * HALF + m * 16; const float rs = rsc ? rsc[row - rbase] : rstd[row];
;                     float v[8];
; #pragma unroll
;                     for (int i = 0; i < 4; ++i) { v[i] = acc[ai][bj][m][0][i] * rs; v[4 + i] = acc[ai][bj][m][1][i] * rs; }
;                     if (seg == 0) {
; #pragma unroll
;                         for (int i = 0; i < 8; ++i) v[i] = v[i] * __builtin_amdgcn_rcpf(1.0f + __expf(-v[i])) * 0.08838834764831845f;
;                     } else if (seg == 1) {
; #pragma unroll
;                         for (int i = 0; i < 8; ++i) { const float s = __builtin_amdgcn_rcpf(1.0f + __expf(-v[i])); v[i] = __logf(lb[i] + (1.0f - lb[i]) * s); }
;                     } else if (seg == 3) {
; #pragma unroll
;                         for (int i = 0; i < 8; ++i) v[i] = v[i] * __builtin_amdgcn_rcpf(1.0f + __expf(-v[i]));
.LBB0_223:
	s_cmp_gt_u32 s80, 1
	s_cselect_b64 s[84:85], -1, 0
	s_cmp_eq_u32 s73, 3
	s_waitcnt vmcnt(0) lgkmcnt(0)
	v_pk_mul_f32 v[62:63], v[62:63], v[68:69] op_sel_hi:[1,0]
	v_pk_mul_f32 v[58:59], v[58:59], v[68:69] op_sel_hi:[1,0]
	v_pk_mul_f32 v[64:65], v[64:65], v[68:69] op_sel_hi:[1,0]
	v_pk_mul_f32 v[60:61], v[60:61], v[68:69] op_sel_hi:[1,0]
	v_cndmask_b32_e64 v68, 0, 1, s[0:1]
	s_cselect_b64 s[82:83], -1, 0
	s_cmp_lt_u32 s80, 2
	s_mov_b64 s[8:9], -1
	v_cmp_ne_u32_e64 s[6:7], 1, v68
	s_cbranch_scc1 .LBB0_230
	s_and_b64 vcc, exec, s[6:7]
	s_mov_b64 s[0:1], -1
	s_cbranch_vccnz .LBB0_227
	s_andn2_b64 vcc, exec, s[82:83]
	s_cbranch_vccnz .LBB0_336
	v_pk_mul_f32 v[68:69], v[62:63], s[100:101] op_sel_hi:[1,0]
	v_pk_mul_f32 v[70:71], v[64:65], s[100:101] op_sel_hi:[1,0]
	v_pk_mul_f32 v[72:73], v[58:59], s[100:101] op_sel_hi:[1,0]
	v_pk_mul_f32 v[78:79], v[60:61], s[100:101] op_sel_hi:[1,0]
	v_exp_f32_e32 v68, v68
	v_exp_f32_e32 v69, v69
	v_exp_f32_e32 v70, v70
	v_exp_f32_e32 v71, v71
	v_exp_f32_e32 v72, v72
	v_exp_f32_e32 v73, v73
	v_exp_f32_e32 v78, v78
	v_exp_f32_e32 v79, v79
	v_pk_add_f32 v[68:69], v[68:69], s[98:99] op_sel_hi:[1,0]
	v_pk_add_f32 v[70:71], v[70:71], s[98:99] op_sel_hi:[1,0]
	v_pk_add_f32 v[72:73], v[72:73], s[98:99] op_sel_hi:[1,0]
	v_pk_add_f32 v[78:79], v[78:79], s[98:99] op_sel_hi:[1,0]
	v_rcp_f32_e32 v68, v68
	v_rcp_f32_e32 v69, v69
	v_rcp_f32_e32 v70, v70
	v_rcp_f32_e32 v71, v71
	v_rcp_f32_e32 v72, v72
	v_rcp_f32_e32 v73, v73
	v_rcp_f32_e32 v78, v78
	v_rcp_f32_e32 v79, v79
	s_nop 0
	v_pk_mul_f32 v[68:69], v[62:63], v[68:69]
	v_pk_mul_f32 v[70:71], v[64:65], v[70:71]
	v_pk_mul_f32 v[72:73], v[58:59], v[72:73]
	v_pk_mul_f32 v[78:79], v[60:61], v[78:79]
	s_mov_b64 s[0:1], 0

;     __device__ __forceinline__ void operator()(const f32x4 (&acc)[2][2][4][2], const Unit& u, int wr, int wc, int fr, int fq) const {
;     ...
;                     if (seg == 0) {
; #pragma unroll
;                         for (int i = 0; i < 8; ++i) v[i] = v[i] * __builtin_amdgcn_rcpf(1.0f + __expf(-v[i])) * 0.08838834764831845f;
.LBB0_230:
	s_andn2_b64 vcc, exec, s[8:9]
	s_cbranch_vccnz .LBB0_232
	v_pk_mul_f32 v[68:69], v[62:63], s[100:101] op_sel_hi:[1,0]
	v_pk_mul_f32 v[70:71], v[64:65], s[100:101] op_sel_hi:[1,0]
	v_pk_mul_f32 v[72:73], v[58:59], s[100:101] op_sel_hi:[1,0]
	v_pk_mul_f32 v[78:79], v[60:61], s[100:101] op_sel_hi:[1,0]
	v_exp_f32_e32 v68, v68
	v_exp_f32_e32 v69, v69
	v_exp_f32_e32 v70, v70
	v_exp_f32_e32 v71, v71
	v_exp_f32_e32 v72, v72
	v_exp_f32_e32 v73, v73
	v_exp_f32_e32 v78, v78
	v_exp_f32_e32 v79, v79
	v_pk_add_f32 v[68:69], v[68:69], s[98:99] op_sel_hi:[1,0]
	v_pk_add_f32 v[70:71], v[70:71], s[98:99] op_sel_hi:[1,0]
	v_pk_add_f32 v[72:73], v[72:73], s[98:99] op_sel_hi:[1,0]
	v_pk_add_f32 v[78:79], v[78:79], s[98:99] op_sel_hi:[1,0]
	v_rcp_f32_e32 v68, v68
	v_rcp_f32_e32 v69, v69
	v_rcp_f32_e32 v70, v70
	v_rcp_f32_e32 v71, v71
	v_rcp_f32_e32 v72, v72
	v_rcp_f32_e32 v73, v73
	v_rcp_f32_e32 v78, v78
	v_rcp_f32_e32 v79, v79
	s_nop 0
	v_pk_mul_f32 v[62:63], v[62:63], v[68:69]
	v_pk_mul_f32 v[64:65], v[64:65], v[70:71]
	v_pk_mul_f32 v[58:59], v[58:59], v[72:73]
	v_pk_mul_f32 v[60:61], v[60:61], v[78:79]
	v_pk_mul_f32 v[72:73], v[58:59], s[70:71] op_sel_hi:[1,0]
	v_pk_mul_f32 v[78:79], v[60:61], s[70:71] op_sel_hi:[1,0]
	v_pk_mul_f32 v[70:71], v[64:65], s[70:71] op_sel_hi:[1,0]
	v_pk_mul_f32 v[68:69], v[62:63], s[70:71] op_sel_hi:[1,0]

;     __device__ __forceinline__ void operator()(const f32x4 (&acc)[2][2][4][2], const Unit& u, int wr, int wc, int fr, int fq) const {
;     ...
;                     for (int i = 0; i < 4; ++i) { v[i] = acc[ai][bj][m][0][i] * rs; v[4 + i] = acc[ai][bj][m][1][i] * rs; }
;                     if (seg == 0) {
; #pragma unroll
;                         for (int i = 0; i < 8; ++i) v[i] = v[i] * __builtin_amdgcn_rcpf(1.0f + __expf(-v[i])) * 0.08838834764831845f;
;                     } else if (seg == 1) {
; #pragma unroll
;                         for (int i = 0; i < 8; ++i) { const float s = __builtin_amdgcn_rcpf(1.0f + __expf(-v[i])); v[i] = __logf(lb[i] + (1.0f - lb[i]) * s); }
;                     } else if (seg == 3) {
; #pragma unroll
;                         for (int i = 0; i < 8; ++i) v[i] = v[i] * __builtin_amdgcn_rcpf(1.0f + __expf(-v[i]));
.LBB0_236:
	s_waitcnt vmcnt(0) lgkmcnt(0)
	v_pk_mul_f32 v[54:55], v[54:55], v[58:59] op_sel_hi:[1,0]
	v_pk_mul_f32 v[50:51], v[50:51], v[58:59] op_sel_hi:[1,0]
	v_pk_mul_f32 v[56:57], v[56:57], v[58:59] op_sel_hi:[1,0]
	v_pk_mul_f32 v[52:53], v[52:53], v[58:59] op_sel_hi:[1,0]
	v_cndmask_b32_e64 v58, 0, 1, s[84:85]
	v_cmp_ne_u32_e64 s[8:9], 1, v58
	s_andn2_b64 vcc, exec, s[84:85]
	s_mov_b64 s[0:1], -1
	s_cbranch_vccnz .LBB0_243
	s_and_b64 vcc, exec, s[6:7]
	s_cbranch_vccnz .LBB0_240
	s_andn2_b64 vcc, exec, s[82:83]
	s_cbranch_vccnz .LBB0_337
	v_pk_mul_f32 v[58:59], v[54:55], s[100:101] op_sel_hi:[1,0]
	v_pk_mul_f32 v[60:61], v[56:57], s[100:101] op_sel_hi:[1,0]
	v_pk_mul_f32 v[62:63], v[50:51], s[100:101] op_sel_hi:[1,0]
	v_pk_mul_f32 v[64:65], v[52:53], s[100:101] op_sel_hi:[1,0]
	v_exp_f32_e32 v58, v58
	v_exp_f32_e32 v59, v59
	v_exp_f32_e32 v60, v60
	v_exp_f32_e32 v61, v61
	v_exp_f32_e32 v62, v62
	v_exp_f32_e32 v63, v63
	v_exp_f32_e32 v64, v64
	v_exp_f32_e32 v65, v65
	v_pk_add_f32 v[58:59], v[58:59], s[98:99] op_sel_hi:[1,0]
	v_pk_add_f32 v[60:61], v[60:61], s[98:99] op_sel_hi:[1,0]
	v_pk_add_f32 v[62:63], v[62:63], s[98:99] op_sel_hi:[1,0]
	v_pk_add_f32 v[64:65], v[64:65], s[98:99] op_sel_hi:[1,0]
	v_rcp_f32_e32 v58, v58
	v_rcp_f32_e32 v59, v59
	v_rcp_f32_e32 v60, v60
	v_rcp_f32_e32 v61, v61
	v_rcp_f32_e32 v62, v62
	v_rcp_f32_e32 v63, v63
	v_rcp_f32_e32 v64, v64
	v_rcp_f32_e32 v65, v65
	s_nop 0
	v_pk_mul_f32 v[58:59], v[54:55], v[58:59]
	v_pk_mul_f32 v[60:61], v[56:57], v[60:61]
	v_pk_mul_f32 v[62:63], v[50:51], v[62:63]
	v_pk_mul_f32 v[64:65], v[52:53], v[64:65]
	s_mov_b64 s[0:1], 0

;     __device__ __forceinline__ void operator()(const f32x4 (&acc)[2][2][4][2], const Unit& u, int wr, int wc, int fr, int fq) const {
;     ...
;                     if (seg == 0) {
; #pragma unroll
;                         for (int i = 0; i < 8; ++i) v[i] = v[i] * __builtin_amdgcn_rcpf(1.0f + __expf(-v[i])) * 0.08838834764831845f;
.LBB0_243:
	s_andn2_b64 vcc, exec, s[0:1]
	s_cbranch_vccnz .LBB0_245
	v_pk_mul_f32 v[58:59], v[54:55], s[100:101] op_sel_hi:[1,0]
	v_pk_mul_f32 v[60:61], v[56:57], s[100:101] op_sel_hi:[1,0]
	v_pk_mul_f32 v[62:63], v[50:51], s[100:101] op_sel_hi:[1,0]
	v_pk_mul_f32 v[64:65], v[52:53], s[100:101] op_sel_hi:[1,0]
	v_exp_f32_e32 v58, v58
	v_exp_f32_e32 v59, v59
	v_exp_f32_e32 v60, v60
	v_exp_f32_e32 v61, v61
	v_exp_f32_e32 v62, v62
	v_exp_f32_e32 v63, v63
	v_exp_f32_e32 v64, v64
	v_exp_f32_e32 v65, v65
	v_pk_add_f32 v[58:59], v[58:59], s[98:99] op_sel_hi:[1,0]
	v_pk_add_f32 v[60:61], v[60:61], s[98:99] op_sel_hi:[1,0]
	v_pk_add_f32 v[62:63], v[62:63], s[98:99] op_sel_hi:[1,0]
	v_pk_add_f32 v[64:65], v[64:65], s[98:99] op_sel_hi:[1,0]
	v_rcp_f32_e32 v58, v58
	v_rcp_f32_e32 v59, v59
	v_rcp_f32_e32 v60, v60
	v_rcp_f32_e32 v61, v61
	v_rcp_f32_e32 v62, v62
	v_rcp_f32_e32 v63, v63
	v_rcp_f32_e32 v64, v64
	v_rcp_f32_e32 v65, v65
	s_nop 0
	v_pk_mul_f32 v[54:55], v[54:55], v[58:59]
	v_pk_mul_f32 v[56:57], v[56:57], v[60:61]
	v_pk_mul_f32 v[50:51], v[50:51], v[62:63]
	v_pk_mul_f32 v[52:53], v[52:53], v[64:65]
	v_pk_mul_f32 v[62:63], v[50:51], s[70:71] op_sel_hi:[1,0]
	v_pk_mul_f32 v[64:65], v[52:53], s[70:71] op_sel_hi:[1,0]
	v_pk_mul_f32 v[60:61], v[56:57], s[70:71] op_sel_hi:[1,0]
	v_pk_mul_f32 v[58:59], v[54:55], s[70:71] op_sel_hi:[1,0]

;     __device__ __forceinline__ void operator()(const f32x4 (&acc)[2][2][4][2], const Unit& u, int wr, int wc, int fr, int fq) const {
;     ...
;                     for (int i = 0; i < 4; ++i) { v[i] = acc[ai][bj][m][0][i] * rs; v[4 + i] = acc[ai][bj][m][1][i] * rs; }
;                     if (seg == 0) {
; #pragma unroll
;                         for (int i = 0; i < 8; ++i) v[i] = v[i] * __builtin_amdgcn_rcpf(1.0f + __expf(-v[i])) * 0.08838834764831845f;
;                     } else if (seg == 1) {
; #pragma unroll
;                         for (int i = 0; i < 8; ++i) { const float s = __builtin_amdgcn_rcpf(1.0f + __expf(-v[i])); v[i] = __logf(lb[i] + (1.0f - lb[i]) * s); }
;                     } else if (seg == 3) {
; #pragma unroll
;                         for (int i = 0; i < 8; ++i) v[i] = v[i] * __builtin_amdgcn_rcpf(1.0f + __expf(-v[i]));
.LBB0_249:
	s_waitcnt vmcnt(0) lgkmcnt(0)
	v_pk_mul_f32 v[46:47], v[46:47], v[50:51] op_sel_hi:[1,0]
	v_pk_mul_f32 v[42:43], v[42:43], v[50:51] op_sel_hi:[1,0]
	v_pk_mul_f32 v[48:49], v[48:49], v[50:51] op_sel_hi:[1,0]
	v_pk_mul_f32 v[44:45], v[44:45], v[50:51] op_sel_hi:[1,0]
	s_and_b64 vcc, exec, s[8:9]
	s_mov_b64 s[0:1], -1
	s_cbranch_vccnz .LBB0_256
	s_and_b64 vcc, exec, s[6:7]
	s_cbranch_vccnz .LBB0_253
	s_andn2_b64 vcc, exec, s[82:83]
	s_cbranch_vccnz .LBB0_338
	v_pk_mul_f32 v[50:51], v[46:47], s[100:101] op_sel_hi:[1,0]
	v_pk_mul_f32 v[52:53], v[48:49], s[100:101] op_sel_hi:[1,0]
	v_pk_mul_f32 v[54:55], v[42:43], s[100:101] op_sel_hi:[1,0]
	v_pk_mul_f32 v[56:57], v[44:45], s[100:101] op_sel_hi:[1,0]
	v_exp_f32_e32 v50, v50
	v_exp_f32_e32 v51, v51
	v_exp_f32_e32 v52, v52
	v_exp_f32_e32 v53, v53
	v_exp_f32_e32 v54, v54
	v_exp_f32_e32 v55, v55
	v_exp_f32_e32 v56, v56
	v_exp_f32_e32 v57, v57
	v_pk_add_f32 v[50:51], v[50:51], s[98:99] op_sel_hi:[1,0]
	v_pk_add_f32 v[52:53], v[52:53], s[98:99] op_sel_hi:[1,0]
	v_pk_add_f32 v[54:55], v[54:55], s[98:99] op_sel_hi:[1,0]
	v_pk_add_f32 v[56:57], v[56:57], s[98:99] op_sel_hi:[1,0]
	v_rcp_f32_e32 v50, v50
	v_rcp_f32_e32 v51, v51
	v_rcp_f32_e32 v52, v52
	v_rcp_f32_e32 v53, v53
	v_rcp_f32_e32 v54, v54
	v_rcp_f32_e32 v55, v55
	v_rcp_f32_e32 v56, v56
	v_rcp_f32_e32 v57, v57
	s_nop 0
	v_pk_mul_f32 v[50:51], v[46:47], v[50:51]
	v_pk_mul_f32 v[52:53], v[48:49], v[52:53]
	v_pk_mul_f32 v[54:55], v[42:43], v[54:55]
	v_pk_mul_f32 v[56:57], v[44:45], v[56:57]
	s_mov_b64 s[0:1], 0

;     __device__ __forceinline__ void operator()(const f32x4 (&acc)[2][2][4][2], const Unit& u, int wr, int wc, int fr, int fq) const {
;     ...
;                     if (seg == 0) {
; #pragma unroll
;                         for (int i = 0; i < 8; ++i) v[i] = v[i] * __builtin_amdgcn_rcpf(1.0f + __expf(-v[i])) * 0.08838834764831845f;
.LBB0_256:
	s_andn2_b64 vcc, exec, s[0:1]
	s_cbranch_vccnz .LBB0_258
	v_pk_mul_f32 v[50:51], v[46:47], s[100:101] op_sel_hi:[1,0]
	v_pk_mul_f32 v[52:53], v[48:49], s[100:101] op_sel_hi:[1,0]
	v_pk_mul_f32 v[54:55], v[42:43], s[100:101] op_sel_hi:[1,0]
	v_pk_mul_f32 v[56:57], v[44:45], s[100:101] op_sel_hi:[1,0]
	v_exp_f32_e32 v50, v50
	v_exp_f32_e32 v51, v51
	v_exp_f32_e32 v52, v52
	v_exp_f32_e32 v53, v53
	v_exp_f32_e32 v54, v54
	v_exp_f32_e32 v55, v55
	v_exp_f32_e32 v56, v56
	v_exp_f32_e32 v57, v57
	v_pk_add_f32 v[50:51], v[50:51], s[98:99] op_sel_hi:[1,0]
	v_pk_add_f32 v[52:53], v[52:53], s[98:99] op_sel_hi:[1,0]
	v_pk_add_f32 v[54:55], v[54:55], s[98:99] op_sel_hi:[1,0]
	v_pk_add_f32 v[56:57], v[56:57], s[98:99] op_sel_hi:[1,0]
	v_rcp_f32_e32 v50, v50
	v_rcp_f32_e32 v51, v51
	v_rcp_f32_e32 v52, v52
	v_rcp_f32_e32 v53, v53
	v_rcp_f32_e32 v54, v54
	v_rcp_f32_e32 v55, v55
	v_rcp_f32_e32 v56, v56
	v_rcp_f32_e32 v57, v57
	s_nop 0
	v_pk_mul_f32 v[46:47], v[46:47], v[50:51]
	v_pk_mul_f32 v[48:49], v[48:49], v[52:53]
	v_pk_mul_f32 v[42:43], v[42:43], v[54:55]
	v_pk_mul_f32 v[44:45], v[44:45], v[56:57]
	v_pk_mul_f32 v[54:55], v[42:43], s[70:71] op_sel_hi:[1,0]
	v_pk_mul_f32 v[56:57], v[44:45], s[70:71] op_sel_hi:[1,0]
	v_pk_mul_f32 v[52:53], v[48:49], s[70:71] op_sel_hi:[1,0]
	v_pk_mul_f32 v[50:51], v[46:47], s[70:71] op_sel_hi:[1,0]

;     __device__ __forceinline__ void operator()(const f32x4 (&acc)[2][2][4][2], const Unit& u, int wr, int wc, int fr, int fq) const {
;     ...
;                     for (int i = 0; i < 4; ++i) { v[i] = acc[ai][bj][m][0][i] * rs; v[4 + i] = acc[ai][bj][m][1][i] * rs; }
;                     if (seg == 0) {
; #pragma unroll
;                         for (int i = 0; i < 8; ++i) v[i] = v[i] * __builtin_amdgcn_rcpf(1.0f + __expf(-v[i])) * 0.08838834764831845f;
;                     } else if (seg == 1) {
; #pragma unroll
;                         for (int i = 0; i < 8; ++i) { const float s = __builtin_amdgcn_rcpf(1.0f + __expf(-v[i])); v[i] = __logf(lb[i] + (1.0f - lb[i]) * s); }
;                     } else if (seg == 3) {
; #pragma unroll
;                         for (int i = 0; i < 8; ++i) v[i] = v[i] * __builtin_amdgcn_rcpf(1.0f + __expf(-v[i]));
.LBB0_262:
	s_waitcnt vmcnt(0) lgkmcnt(0)
	v_pk_mul_f32 v[38:39], v[38:39], v[42:43] op_sel_hi:[1,0]
	v_pk_mul_f32 v[34:35], v[34:35], v[42:43] op_sel_hi:[1,0]
	v_pk_mul_f32 v[40:41], v[40:41], v[42:43] op_sel_hi:[1,0]
	v_pk_mul_f32 v[36:37], v[36:37], v[42:43] op_sel_hi:[1,0]
	s_and_b64 vcc, exec, s[8:9]
	s_mov_b64 s[0:1], -1
	s_cbranch_vccnz .LBB0_269
	s_and_b64 vcc, exec, s[6:7]
	s_cbranch_vccnz .LBB0_266
	s_andn2_b64 vcc, exec, s[82:83]
	s_cbranch_vccnz .LBB0_339
	v_pk_mul_f32 v[42:43], v[38:39], s[100:101] op_sel_hi:[1,0]
	v_pk_mul_f32 v[44:45], v[40:41], s[100:101] op_sel_hi:[1,0]
	v_pk_mul_f32 v[46:47], v[34:35], s[100:101] op_sel_hi:[1,0]
	v_pk_mul_f32 v[48:49], v[36:37], s[100:101] op_sel_hi:[1,0]
	v_exp_f32_e32 v42, v42
	v_exp_f32_e32 v43, v43
	v_exp_f32_e32 v44, v44
	v_exp_f32_e32 v45, v45
	v_exp_f32_e32 v46, v46
	v_exp_f32_e32 v47, v47
	v_exp_f32_e32 v48, v48
	v_exp_f32_e32 v49, v49
	v_pk_add_f32 v[42:43], v[42:43], s[98:99] op_sel_hi:[1,0]
	v_pk_add_f32 v[44:45], v[44:45], s[98:99] op_sel_hi:[1,0]
	v_pk_add_f32 v[46:47], v[46:47], s[98:99] op_sel_hi:[1,0]
	v_pk_add_f32 v[48:49], v[48:49], s[98:99] op_sel_hi:[1,0]
	v_rcp_f32_e32 v42, v42
	v_rcp_f32_e32 v43, v43
	v_rcp_f32_e32 v44, v44
	v_rcp_f32_e32 v45, v45
	v_rcp_f32_e32 v46, v46
	v_rcp_f32_e32 v47, v47
	v_rcp_f32_e32 v48, v48
	v_rcp_f32_e32 v49, v49
	s_nop 0
	v_pk_mul_f32 v[42:43], v[38:39], v[42:43]
	v_pk_mul_f32 v[44:45], v[40:41], v[44:45]
	v_pk_mul_f32 v[46:47], v[34:35], v[46:47]
	v_pk_mul_f32 v[48:49], v[36:37], v[48:49]
	s_mov_b64 s[0:1], 0

;     __device__ __forceinline__ void operator()(const f32x4 (&acc)[2][2][4][2], const Unit& u, int wr, int wc, int fr, int fq) const {
;     ...
;                     if (seg == 0) {
; #pragma unroll
;                         for (int i = 0; i < 8; ++i) v[i] = v[i] * __builtin_amdgcn_rcpf(1.0f + __expf(-v[i])) * 0.08838834764831845f;
.LBB0_269:
	s_andn2_b64 vcc, exec, s[0:1]
	s_cbranch_vccnz .LBB0_271
	v_pk_mul_f32 v[42:43], v[38:39], s[100:101] op_sel_hi:[1,0]
	v_pk_mul_f32 v[44:45], v[40:41], s[100:101] op_sel_hi:[1,0]
	v_pk_mul_f32 v[46:47], v[34:35], s[100:101] op_sel_hi:[1,0]
	v_pk_mul_f32 v[48:49], v[36:37], s[100:101] op_sel_hi:[1,0]
	v_exp_f32_e32 v42, v42
	v_exp_f32_e32 v43, v43
	v_exp_f32_e32 v44, v44
	v_exp_f32_e32 v45, v45
	v_exp_f32_e32 v46, v46
	v_exp_f32_e32 v47, v47
	v_exp_f32_e32 v48, v48
	v_exp_f32_e32 v49, v49
	v_pk_add_f32 v[42:43], v[42:43], s[98:99] op_sel_hi:[1,0]
	v_pk_add_f32 v[44:45], v[44:45], s[98:99] op_sel_hi:[1,0]
	v_pk_add_f32 v[46:47], v[46:47], s[98:99] op_sel_hi:[1,0]
	v_pk_add_f32 v[48:49], v[48:49], s[98:99] op_sel_hi:[1,0]
	v_rcp_f32_e32 v42, v42
	v_rcp_f32_e32 v43, v43
	v_rcp_f32_e32 v44, v44
	v_rcp_f32_e32 v45, v45
	v_rcp_f32_e32 v46, v46
	v_rcp_f32_e32 v47, v47
	v_rcp_f32_e32 v48, v48
	v_rcp_f32_e32 v49, v49
	s_nop 0
	v_pk_mul_f32 v[38:39], v[38:39], v[42:43]
	v_pk_mul_f32 v[40:41], v[40:41], v[44:45]
	v_pk_mul_f32 v[34:35], v[34:35], v[46:47]
	v_pk_mul_f32 v[36:37], v[36:37], v[48:49]
	v_pk_mul_f32 v[46:47], v[34:35], s[70:71] op_sel_hi:[1,0]
	v_pk_mul_f32 v[48:49], v[36:37], s[70:71] op_sel_hi:[1,0]
	v_pk_mul_f32 v[44:45], v[40:41], s[70:71] op_sel_hi:[1,0]
	v_pk_mul_f32 v[42:43], v[38:39], s[70:71] op_sel_hi:[1,0]

;     __device__ __forceinline__ void operator()(const f32x4 (&acc)[2][2][4][2], const Unit& u, int wr, int wc, int fr, int fq) const {
;     ...
;                     for (int i = 0; i < 4; ++i) { v[i] = acc[ai][bj][m][0][i] * rs; v[4 + i] = acc[ai][bj][m][1][i] * rs; }
;                     if (seg == 0) {
; #pragma unroll
;                         for (int i = 0; i < 8; ++i) v[i] = v[i] * __builtin_amdgcn_rcpf(1.0f + __expf(-v[i])) * 0.08838834764831845f;
;                     } else if (seg == 1) {
; #pragma unroll
;                         for (int i = 0; i < 8; ++i) { const float s = __builtin_amdgcn_rcpf(1.0f + __expf(-v[i])); v[i] = __logf(lb[i] + (1.0f - lb[i]) * s); }
;                     } else if (seg == 3) {
; #pragma unroll
;                         for (int i = 0; i < 8; ++i) v[i] = v[i] * __builtin_amdgcn_rcpf(1.0f + __expf(-v[i]));
.LBB0_275:
	s_waitcnt vmcnt(0) lgkmcnt(0)
	v_pk_mul_f32 v[30:31], v[30:31], v[34:35] op_sel_hi:[1,0]
	v_pk_mul_f32 v[26:27], v[26:27], v[34:35] op_sel_hi:[1,0]
	v_pk_mul_f32 v[32:33], v[32:33], v[34:35] op_sel_hi:[1,0]
	v_pk_mul_f32 v[28:29], v[28:29], v[34:35] op_sel_hi:[1,0]
	s_and_b64 vcc, exec, s[8:9]
	s_mov_b64 s[0:1], -1
	s_cbranch_vccnz .LBB0_282
	s_and_b64 vcc, exec, s[6:7]
	s_cbranch_vccnz .LBB0_279
	s_andn2_b64 vcc, exec, s[82:83]
	s_cbranch_vccnz .LBB0_340
	v_pk_mul_f32 v[34:35], v[30:31], s[100:101] op_sel_hi:[1,0]
	v_pk_mul_f32 v[36:37], v[32:33], s[100:101] op_sel_hi:[1,0]
	v_pk_mul_f32 v[38:39], v[26:27], s[100:101] op_sel_hi:[1,0]
	v_pk_mul_f32 v[40:41], v[28:29], s[100:101] op_sel_hi:[1,0]
	v_exp_f32_e32 v34, v34
	v_exp_f32_e32 v35, v35
	v_exp_f32_e32 v36, v36
	v_exp_f32_e32 v37, v37
	v_exp_f32_e32 v38, v38
	v_exp_f32_e32 v39, v39
	v_exp_f32_e32 v40, v40
	v_exp_f32_e32 v41, v41
	v_pk_add_f32 v[34:35], v[34:35], s[98:99] op_sel_hi:[1,0]
	v_pk_add_f32 v[36:37], v[36:37], s[98:99] op_sel_hi:[1,0]
	v_pk_add_f32 v[38:39], v[38:39], s[98:99] op_sel_hi:[1,0]
	v_pk_add_f32 v[40:41], v[40:41], s[98:99] op_sel_hi:[1,0]
	v_rcp_f32_e32 v34, v34
	v_rcp_f32_e32 v35, v35
	v_rcp_f32_e32 v36, v36
	v_rcp_f32_e32 v37, v37
	v_rcp_f32_e32 v38, v38
	v_rcp_f32_e32 v39, v39
	v_rcp_f32_e32 v40, v40
	v_rcp_f32_e32 v41, v41
	s_nop 0
	v_pk_mul_f32 v[34:35], v[30:31], v[34:35]
	v_pk_mul_f32 v[36:37], v[32:33], v[36:37]
	v_pk_mul_f32 v[38:39], v[26:27], v[38:39]
	v_pk_mul_f32 v[40:41], v[28:29], v[40:41]
	s_mov_b64 s[0:1], 0

;     __device__ __forceinline__ void operator()(const f32x4 (&acc)[2][2][4][2], const Unit& u, int wr, int wc, int fr, int fq) const {
;     ...
;                     if (seg == 0) {
; #pragma unroll
;                         for (int i = 0; i < 8; ++i) v[i] = v[i] * __builtin_amdgcn_rcpf(1.0f + __expf(-v[i])) * 0.08838834764831845f;
.LBB0_282:
	s_andn2_b64 vcc, exec, s[0:1]
	s_cbranch_vccnz .LBB0_284
	v_pk_mul_f32 v[34:35], v[30:31], s[100:101] op_sel_hi:[1,0]
	v_pk_mul_f32 v[36:37], v[32:33], s[100:101] op_sel_hi:[1,0]
	v_pk_mul_f32 v[38:39], v[26:27], s[100:101] op_sel_hi:[1,0]
	v_pk_mul_f32 v[40:41], v[28:29], s[100:101] op_sel_hi:[1,0]
	v_exp_f32_e32 v34, v34
	v_exp_f32_e32 v35, v35
	v_exp_f32_e32 v36, v36
	v_exp_f32_e32 v37, v37
	v_exp_f32_e32 v38, v38
	v_exp_f32_e32 v39, v39
	v_exp_f32_e32 v40, v40
	v_exp_f32_e32 v41, v41
	v_pk_add_f32 v[34:35], v[34:35], s[98:99] op_sel_hi:[1,0]
	v_pk_add_f32 v[36:37], v[36:37], s[98:99] op_sel_hi:[1,0]
	v_pk_add_f32 v[38:39], v[38:39], s[98:99] op_sel_hi:[1,0]
	v_pk_add_f32 v[40:41], v[40:41], s[98:99] op_sel_hi:[1,0]
	v_rcp_f32_e32 v34, v34
	v_rcp_f32_e32 v35, v35
	v_rcp_f32_e32 v36, v36
	v_rcp_f32_e32 v37, v37
	v_rcp_f32_e32 v38, v38
	v_rcp_f32_e32 v39, v39
	v_rcp_f32_e32 v40, v40
	v_rcp_f32_e32 v41, v41
	s_nop 0
	v_pk_mul_f32 v[30:31], v[30:31], v[34:35]
	v_pk_mul_f32 v[32:33], v[32:33], v[36:37]
	v_pk_mul_f32 v[26:27], v[26:27], v[38:39]
	v_pk_mul_f32 v[28:29], v[28:29], v[40:41]
	v_pk_mul_f32 v[38:39], v[26:27], s[70:71] op_sel_hi:[1,0]
	v_pk_mul_f32 v[40:41], v[28:29], s[70:71] op_sel_hi:[1,0]
	v_pk_mul_f32 v[36:37], v[32:33], s[70:71] op_sel_hi:[1,0]
	v_pk_mul_f32 v[34:35], v[30:31], s[70:71] op_sel_hi:[1,0]

;     __device__ __forceinline__ void operator()(const f32x4 (&acc)[2][2][4][2], const Unit& u, int wr, int wc, int fr, int fq) const {
;     ...
;                     for (int i = 0; i < 4; ++i) { v[i] = acc[ai][bj][m][0][i] * rs; v[4 + i] = acc[ai][bj][m][1][i] * rs; }
;                     if (seg == 0) {
; #pragma unroll
;                         for (int i = 0; i < 8; ++i) v[i] = v[i] * __builtin_amdgcn_rcpf(1.0f + __expf(-v[i])) * 0.08838834764831845f;
;                     } else if (seg == 1) {
; #pragma unroll
;                         for (int i = 0; i < 8; ++i) { const float s = __builtin_amdgcn_rcpf(1.0f + __expf(-v[i])); v[i] = __logf(lb[i] + (1.0f - lb[i]) * s); }
;                     } else if (seg == 3) {
; #pragma unroll
;                         for (int i = 0; i < 8; ++i) v[i] = v[i] * __builtin_amdgcn_rcpf(1.0f + __expf(-v[i]));
.LBB0_288:
	s_waitcnt vmcnt(0) lgkmcnt(0)
	v_pk_mul_f32 v[22:23], v[22:23], v[26:27] op_sel_hi:[1,0]
	v_pk_mul_f32 v[18:19], v[18:19], v[26:27] op_sel_hi:[1,0]
	v_pk_mul_f32 v[24:25], v[24:25], v[26:27] op_sel_hi:[1,0]
	v_pk_mul_f32 v[20:21], v[20:21], v[26:27] op_sel_hi:[1,0]
	s_and_b64 vcc, exec, s[8:9]
	s_mov_b64 s[0:1], -1
	s_cbranch_vccnz .LBB0_295
	s_and_b64 vcc, exec, s[6:7]
	s_cbranch_vccnz .LBB0_292
	s_andn2_b64 vcc, exec, s[82:83]
	s_cbranch_vccnz .LBB0_341
	v_pk_mul_f32 v[26:27], v[22:23], s[100:101] op_sel_hi:[1,0]
	v_pk_mul_f32 v[28:29], v[24:25], s[100:101] op_sel_hi:[1,0]
	v_pk_mul_f32 v[30:31], v[18:19], s[100:101] op_sel_hi:[1,0]
	v_pk_mul_f32 v[32:33], v[20:21], s[100:101] op_sel_hi:[1,0]
	v_exp_f32_e32 v26, v26
	v_exp_f32_e32 v27, v27
	v_exp_f32_e32 v28, v28
	v_exp_f32_e32 v29, v29
	v_exp_f32_e32 v30, v30
	v_exp_f32_e32 v31, v31
	v_exp_f32_e32 v32, v32
	v_exp_f32_e32 v33, v33
	v_pk_add_f32 v[26:27], v[26:27], s[98:99] op_sel_hi:[1,0]
	v_pk_add_f32 v[28:29], v[28:29], s[98:99] op_sel_hi:[1,0]
	v_pk_add_f32 v[30:31], v[30:31], s[98:99] op_sel_hi:[1,0]
	v_pk_add_f32 v[32:33], v[32:33], s[98:99] op_sel_hi:[1,0]
	v_rcp_f32_e32 v26, v26
	v_rcp_f32_e32 v27, v27
	v_rcp_f32_e32 v28, v28
	v_rcp_f32_e32 v29, v29
	v_rcp_f32_e32 v30, v30
	v_rcp_f32_e32 v31, v31
	v_rcp_f32_e32 v32, v32
	v_rcp_f32_e32 v33, v33
	s_nop 0
	v_pk_mul_f32 v[26:27], v[22:23], v[26:27]
	v_pk_mul_f32 v[28:29], v[24:25], v[28:29]
	v_pk_mul_f32 v[30:31], v[18:19], v[30:31]
	v_pk_mul_f32 v[32:33], v[20:21], v[32:33]
	s_mov_b64 s[0:1], 0

;     __device__ __forceinline__ void operator()(const f32x4 (&acc)[2][2][4][2], const Unit& u, int wr, int wc, int fr, int fq) const {
;     ...
;                     if (seg == 0) {
; #pragma unroll
;                         for (int i = 0; i < 8; ++i) v[i] = v[i] * __builtin_amdgcn_rcpf(1.0f + __expf(-v[i])) * 0.08838834764831845f;
.LBB0_295:
	s_andn2_b64 vcc, exec, s[0:1]
	s_cbranch_vccnz .LBB0_297
	v_pk_mul_f32 v[26:27], v[22:23], s[100:101] op_sel_hi:[1,0]
	v_pk_mul_f32 v[28:29], v[24:25], s[100:101] op_sel_hi:[1,0]
	v_pk_mul_f32 v[30:31], v[18:19], s[100:101] op_sel_hi:[1,0]
	v_pk_mul_f32 v[32:33], v[20:21], s[100:101] op_sel_hi:[1,0]
	v_exp_f32_e32 v26, v26
	v_exp_f32_e32 v27, v27
	v_exp_f32_e32 v28, v28
	v_exp_f32_e32 v29, v29
	v_exp_f32_e32 v30, v30
	v_exp_f32_e32 v31, v31
	v_exp_f32_e32 v32, v32
	v_exp_f32_e32 v33, v33
	v_pk_add_f32 v[26:27], v[26:27], s[98:99] op_sel_hi:[1,0]
	v_pk_add_f32 v[28:29], v[28:29], s[98:99] op_sel_hi:[1,0]
	v_pk_add_f32 v[30:31], v[30:31], s[98:99] op_sel_hi:[1,0]
	v_pk_add_f32 v[32:33], v[32:33], s[98:99] op_sel_hi:[1,0]
	v_rcp_f32_e32 v26, v26
	v_rcp_f32_e32 v27, v27
	v_rcp_f32_e32 v28, v28
	v_rcp_f32_e32 v29, v29
	v_rcp_f32_e32 v30, v30
	v_rcp_f32_e32 v31, v31
	v_rcp_f32_e32 v32, v32
	v_rcp_f32_e32 v33, v33
	s_nop 0
	v_pk_mul_f32 v[22:23], v[22:23], v[26:27]
	v_pk_mul_f32 v[24:25], v[24:25], v[28:29]
	v_pk_mul_f32 v[18:19], v[18:19], v[30:31]
	v_pk_mul_f32 v[20:21], v[20:21], v[32:33]
	v_pk_mul_f32 v[30:31], v[18:19], s[70:71] op_sel_hi:[1,0]
	v_pk_mul_f32 v[32:33], v[20:21], s[70:71] op_sel_hi:[1,0]
	v_pk_mul_f32 v[28:29], v[24:25], s[70:71] op_sel_hi:[1,0]
	v_pk_mul_f32 v[26:27], v[22:23], s[70:71] op_sel_hi:[1,0]

;     __device__ __forceinline__ void operator()(const f32x4 (&acc)[2][2][4][2], const Unit& u, int wr, int wc, int fr, int fq) const {
;     ...
;                     for (int i = 0; i < 4; ++i) { v[i] = acc[ai][bj][m][0][i] * rs; v[4 + i] = acc[ai][bj][m][1][i] * rs; }
;                     if (seg == 0) {
; #pragma unroll
;                         for (int i = 0; i < 8; ++i) v[i] = v[i] * __builtin_amdgcn_rcpf(1.0f + __expf(-v[i])) * 0.08838834764831845f;
;                     } else if (seg == 1) {
; #pragma unroll
;                         for (int i = 0; i < 8; ++i) { const float s = __builtin_amdgcn_rcpf(1.0f + __expf(-v[i])); v[i] = __logf(lb[i] + (1.0f - lb[i]) * s); }
;                     } else if (seg == 3) {
; #pragma unroll
;                         for (int i = 0; i < 8; ++i) v[i] = v[i] * __builtin_amdgcn_rcpf(1.0f + __expf(-v[i]));
.LBB0_301:
	s_waitcnt vmcnt(0) lgkmcnt(0)
	v_pk_mul_f32 v[14:15], v[14:15], v[18:19] op_sel_hi:[1,0]
	v_pk_mul_f32 v[10:11], v[10:11], v[18:19] op_sel_hi:[1,0]
	v_pk_mul_f32 v[16:17], v[16:17], v[18:19] op_sel_hi:[1,0]
	v_pk_mul_f32 v[12:13], v[12:13], v[18:19] op_sel_hi:[1,0]
	s_and_b64 vcc, exec, s[8:9]
	s_mov_b64 s[0:1], -1
	s_cbranch_vccnz .LBB0_308
	s_and_b64 vcc, exec, s[6:7]
	s_cbranch_vccnz .LBB0_305
	s_andn2_b64 vcc, exec, s[82:83]
	s_cbranch_vccnz .LBB0_342
	v_pk_mul_f32 v[18:19], v[14:15], s[100:101] op_sel_hi:[1,0]
	v_pk_mul_f32 v[20:21], v[16:17], s[100:101] op_sel_hi:[1,0]
	v_pk_mul_f32 v[22:23], v[10:11], s[100:101] op_sel_hi:[1,0]
	v_pk_mul_f32 v[24:25], v[12:13], s[100:101] op_sel_hi:[1,0]
	v_exp_f32_e32 v18, v18
	v_exp_f32_e32 v19, v19
	v_exp_f32_e32 v20, v20
	v_exp_f32_e32 v21, v21
	v_exp_f32_e32 v22, v22
	v_exp_f32_e32 v23, v23
	v_exp_f32_e32 v24, v24
	v_exp_f32_e32 v25, v25
	v_pk_add_f32 v[18:19], v[18:19], s[98:99] op_sel_hi:[1,0]
	v_pk_add_f32 v[20:21], v[20:21], s[98:99] op_sel_hi:[1,0]
	v_pk_add_f32 v[22:23], v[22:23], s[98:99] op_sel_hi:[1,0]
	v_pk_add_f32 v[24:25], v[24:25], s[98:99] op_sel_hi:[1,0]
	v_rcp_f32_e32 v18, v18
	v_rcp_f32_e32 v19, v19
	v_rcp_f32_e32 v20, v20
	v_rcp_f32_e32 v21, v21
	v_rcp_f32_e32 v22, v22
	v_rcp_f32_e32 v23, v23
	v_rcp_f32_e32 v24, v24
	v_rcp_f32_e32 v25, v25
	s_nop 0
	v_pk_mul_f32 v[18:19], v[14:15], v[18:19]
	v_pk_mul_f32 v[20:21], v[16:17], v[20:21]
	v_pk_mul_f32 v[22:23], v[10:11], v[22:23]
	v_pk_mul_f32 v[24:25], v[12:13], v[24:25]
	s_mov_b64 s[0:1], 0

;     __device__ __forceinline__ void operator()(const f32x4 (&acc)[2][2][4][2], const Unit& u, int wr, int wc, int fr, int fq) const {
;     ...
;                     if (seg == 0) {
; #pragma unroll
;                         for (int i = 0; i < 8; ++i) v[i] = v[i] * __builtin_amdgcn_rcpf(1.0f + __expf(-v[i])) * 0.08838834764831845f;
.LBB0_308:
	s_andn2_b64 vcc, exec, s[0:1]
	s_cbranch_vccnz .LBB0_310
	v_pk_mul_f32 v[18:19], v[14:15], s[100:101] op_sel_hi:[1,0]
	v_pk_mul_f32 v[20:21], v[16:17], s[100:101] op_sel_hi:[1,0]
	v_pk_mul_f32 v[22:23], v[10:11], s[100:101] op_sel_hi:[1,0]
	v_pk_mul_f32 v[24:25], v[12:13], s[100:101] op_sel_hi:[1,0]
	v_exp_f32_e32 v18, v18
	v_exp_f32_e32 v19, v19
	v_exp_f32_e32 v20, v20
	v_exp_f32_e32 v21, v21
	v_exp_f32_e32 v22, v22
	v_exp_f32_e32 v23, v23
	v_exp_f32_e32 v24, v24
	v_exp_f32_e32 v25, v25
	v_pk_add_f32 v[18:19], v[18:19], s[98:99] op_sel_hi:[1,0]
	v_pk_add_f32 v[20:21], v[20:21], s[98:99] op_sel_hi:[1,0]
	v_pk_add_f32 v[22:23], v[22:23], s[98:99] op_sel_hi:[1,0]
	v_pk_add_f32 v[24:25], v[24:25], s[98:99] op_sel_hi:[1,0]
	v_rcp_f32_e32 v18, v18
	v_rcp_f32_e32 v19, v19
	v_rcp_f32_e32 v20, v20
	v_rcp_f32_e32 v21, v21
	v_rcp_f32_e32 v22, v22
	v_rcp_f32_e32 v23, v23
	v_rcp_f32_e32 v24, v24
	v_rcp_f32_e32 v25, v25
	s_nop 0
	v_pk_mul_f32 v[14:15], v[14:15], v[18:19]
	v_pk_mul_f32 v[16:17], v[16:17], v[20:21]
	v_pk_mul_f32 v[10:11], v[10:11], v[22:23]
	v_pk_mul_f32 v[12:13], v[12:13], v[24:25]
	v_pk_mul_f32 v[22:23], v[10:11], s[70:71] op_sel_hi:[1,0]
	v_pk_mul_f32 v[24:25], v[12:13], s[70:71] op_sel_hi:[1,0]
	v_pk_mul_f32 v[20:21], v[16:17], s[70:71] op_sel_hi:[1,0]
	v_pk_mul_f32 v[18:19], v[14:15], s[70:71] op_sel_hi:[1,0]

;     __device__ __forceinline__ void operator()(const f32x4 (&acc)[2][2][4][2], const Unit& u, int wr, int wc, int fr, int fq) const {
;     ...
;                     for (int i = 0; i < 4; ++i) { v[i] = acc[ai][bj][m][0][i] * rs; v[4 + i] = acc[ai][bj][m][1][i] * rs; }
;                     if (seg == 0) {
; #pragma unroll
;                         for (int i = 0; i < 8; ++i) v[i] = v[i] * __builtin_amdgcn_rcpf(1.0f + __expf(-v[i])) * 0.08838834764831845f;
;                     } else if (seg == 1) {
; #pragma unroll
;                         for (int i = 0; i < 8; ++i) { const float s = __builtin_amdgcn_rcpf(1.0f + __expf(-v[i])); v[i] = __logf(lb[i] + (1.0f - lb[i]) * s); }
;                     } else if (seg == 3) {
; #pragma unroll
;                         for (int i = 0; i < 8; ++i) v[i] = v[i] * __builtin_amdgcn_rcpf(1.0f + __expf(-v[i]));
.LBB0_314:
	s_waitcnt vmcnt(0) lgkmcnt(0)
	v_pk_mul_f32 v[6:7], v[6:7], v[10:11] op_sel_hi:[1,0]
	v_pk_mul_f32 v[2:3], v[2:3], v[10:11] op_sel_hi:[1,0]
	v_pk_mul_f32 v[8:9], v[8:9], v[10:11] op_sel_hi:[1,0]
	v_pk_mul_f32 v[4:5], v[4:5], v[10:11] op_sel_hi:[1,0]
	s_and_b64 vcc, exec, s[8:9]
	s_mov_b64 s[0:1], -1
	s_cbranch_vccnz .LBB0_321
	s_and_b64 vcc, exec, s[6:7]
	s_cbranch_vccnz .LBB0_318
	s_andn2_b64 vcc, exec, s[82:83]
	s_cbranch_vccnz .LBB0_343
	v_pk_mul_f32 v[10:11], v[6:7], s[100:101] op_sel_hi:[1,0]
	v_pk_mul_f32 v[12:13], v[8:9], s[100:101] op_sel_hi:[1,0]
	v_pk_mul_f32 v[14:15], v[2:3], s[100:101] op_sel_hi:[1,0]
	v_pk_mul_f32 v[16:17], v[4:5], s[100:101] op_sel_hi:[1,0]
	v_exp_f32_e32 v10, v10
	v_exp_f32_e32 v11, v11
	v_exp_f32_e32 v12, v12
	v_exp_f32_e32 v13, v13
	v_exp_f32_e32 v14, v14
	v_exp_f32_e32 v15, v15
	v_exp_f32_e32 v16, v16
	v_exp_f32_e32 v17, v17
	v_pk_add_f32 v[10:11], v[10:11], s[98:99] op_sel_hi:[1,0]
	v_pk_add_f32 v[12:13], v[12:13], s[98:99] op_sel_hi:[1,0]
	v_pk_add_f32 v[14:15], v[14:15], s[98:99] op_sel_hi:[1,0]
	v_pk_add_f32 v[16:17], v[16:17], s[98:99] op_sel_hi:[1,0]
	v_rcp_f32_e32 v10, v10
	v_rcp_f32_e32 v11, v11
	v_rcp_f32_e32 v12, v12
	v_rcp_f32_e32 v13, v13
	v_rcp_f32_e32 v14, v14
	v_rcp_f32_e32 v15, v15
	v_rcp_f32_e32 v16, v16
	v_rcp_f32_e32 v17, v17
	s_nop 0
	v_pk_mul_f32 v[10:11], v[6:7], v[10:11]
	v_pk_mul_f32 v[12:13], v[8:9], v[12:13]
	v_pk_mul_f32 v[14:15], v[2:3], v[14:15]
	v_pk_mul_f32 v[16:17], v[4:5], v[16:17]
	s_mov_b64 s[0:1], 0

;     __device__ __forceinline__ void operator()(const f32x4 (&acc)[2][2][4][2], const Unit& u, int wr, int wc, int fr, int fq) const {
;     ...
;                     if (seg == 0) {
; #pragma unroll
;                         for (int i = 0; i < 8; ++i) v[i] = v[i] * __builtin_amdgcn_rcpf(1.0f + __expf(-v[i])) * 0.08838834764831845f;
.LBB0_321:
	s_andn2_b64 vcc, exec, s[0:1]
	s_cbranch_vccnz .LBB0_323
	v_pk_mul_f32 v[10:11], v[6:7], s[100:101] op_sel_hi:[1,0]
	v_pk_mul_f32 v[12:13], v[8:9], s[100:101] op_sel_hi:[1,0]
	v_pk_mul_f32 v[14:15], v[2:3], s[100:101] op_sel_hi:[1,0]
	v_pk_mul_f32 v[16:17], v[4:5], s[100:101] op_sel_hi:[1,0]
	v_exp_f32_e32 v10, v10
	v_exp_f32_e32 v11, v11
	v_exp_f32_e32 v12, v12
	v_exp_f32_e32 v13, v13
	v_exp_f32_e32 v14, v14
	v_exp_f32_e32 v15, v15
	v_exp_f32_e32 v16, v16
	v_exp_f32_e32 v17, v17
	v_pk_add_f32 v[10:11], v[10:11], s[98:99] op_sel_hi:[1,0]
	v_pk_add_f32 v[12:13], v[12:13], s[98:99] op_sel_hi:[1,0]
	v_pk_add_f32 v[14:15], v[14:15], s[98:99] op_sel_hi:[1,0]
	v_pk_add_f32 v[16:17], v[16:17], s[98:99] op_sel_hi:[1,0]
	v_rcp_f32_e32 v10, v10
	v_rcp_f32_e32 v11, v11
	v_rcp_f32_e32 v12, v12
	v_rcp_f32_e32 v13, v13
	v_rcp_f32_e32 v14, v14
	v_rcp_f32_e32 v15, v15
	v_rcp_f32_e32 v16, v16
	v_rcp_f32_e32 v17, v17
	s_nop 0
	v_pk_mul_f32 v[6:7], v[6:7], v[10:11]
	v_pk_mul_f32 v[8:9], v[8:9], v[12:13]
	v_pk_mul_f32 v[2:3], v[2:3], v[14:15]
	v_pk_mul_f32 v[4:5], v[4:5], v[16:17]
	v_pk_mul_f32 v[14:15], v[2:3], s[70:71] op_sel_hi:[1,0]
	v_pk_mul_f32 v[16:17], v[4:5], s[70:71] op_sel_hi:[1,0]
	v_pk_mul_f32 v[12:13], v[8:9], s[70:71] op_sel_hi:[1,0]
	v_pk_mul_f32 v[10:11], v[6:7], s[70:71] op_sel_hi:[1,0]
